# nt (streaming) cache hint on the read-once f32 input loads of phase 0 (weights, x, mem)
# speedup vs baseline: 1.0141x; 1.0141x over previous
; #define LAS __attribute__((address_space(3)))
; #define SCHED_FENCE() __builtin_amdgcn_sched_barrier(0)
; __device__ __forceinline__ void transpose_item(const float* W, int K, int N, bf16_t* WT, int kb, int nbd, int src0, LAS float* scr, int lane, const float* gk = nullptr) {
;     const int k0 = kb * 64;
;     const float* wp = W + (size_t)(k0 + (lane >> 4)) * N + src0 + (lane & 15) * 4;
;     f32x4 v[16];
; #pragma unroll
;     for (int i = 0; i < 16; ++i) v[i] = *(const f32x4*)(wp + (size_t)(4 * i) * N);
;     SCHED_FENCE();
; #pragma unroll
;     for (int i = 0; i < 16; ++i) { if (gk) v[i] = v[i] * gk[k0 + 4 * i + (lane >> 4)];
;         LAS float* s = scr + (4 * i + (lane >> 4)) * 65 + (lane & 15) * 4; s[0] = v[i].x; s[1] = v[i].y; s[2] = v[i].z; s[3] = v[i].w; }
; __global__ void __launch_bounds__(512, 2) fwd_kernel(Args a) {
;     ...
;             for (int it = gw; it < NITEMS; it += ngw) {
;                 int r = it;
;                 if (r < I_GU) { const int nb = r % 176; transpose_item(P.in[3], DM, NGU, (bf16_t*)(ws + WS_WGU1), r / 176, nb, map_gu(nb), scr, lane, P.in[2]); continue; } r -= I_GU;
;                 if (r < I_GU) { const int nb = r % 176; transpose_item(P.in[21], DM, NGU, (bf16_t*)(ws + WS_WGU2), r / 176, nb, map_gu(nb), scr, lane, P.in[20]); continue; } r -= I_GU;
;                 if (r < I_D) { const int nb = r % 32; transpose_item(P.in[4], DFF, DM, (bf16_t*)(ws + WS_WD1), r / 32, nb, nb * 64, scr, lane); continue; } r -= I_D;
;                 if (r < I_D) { const int nb = r % 32; transpose_item(P.in[22], DFF, DM, (bf16_t*)(ws + WS_WD2), r / 32, nb, nb * 64, scr, lane); continue; } r -= I_D;
;                 if (r < I_IN) { const int nb = r % 72; transpose_item(P.in[8], DM, 4608, (bf16_t*)(ws + WS_WIN), r / 72, nb, map_win(nb), scr, lane, P.in[6]); continue; } r -= I_IN;
;                 if (r < I_MKV) { const int nb = r % 16; transpose_item(P.in[9], DM, 1024, (bf16_t*)(ws + WS_WMKV), r / 16, nb, nb * 64, scr, lane); continue; } r -= I_MKV;
;                 { const int nb = r % 32; transpose_item(P.in[18], DM, DM, (bf16_t*)(ws + WS_WOUT), r / 32, nb, nb * 64, scr, lane); }
.LBB0_258:
	s_cmpk_gt_i32 s28, 0x15ff
	s_mov_b64 s[6:7], -1
	s_cbranch_scc0 .LBB0_337
	s_cmpk_gt_u32 s28, 0x2bff
	s_cbranch_scc0 .LBB0_310
	s_cmpk_gt_u32 s28, 0x36ff
	s_cbranch_scc0 .LBB0_307
	s_cmpk_gt_u32 s28, 0x41ff
	s_cbranch_scc0 .LBB0_304
	s_cmpk_gt_u32 s28, 0x4aff
	s_cbranch_scc0 .LBB0_268
	s_cmpk_gt_u32 s28, 0x4cff
	s_cbranch_scc0 .LBB0_265
	s_load_dwordx2 s[30:31], s[40:41], 0x90
	s_and_b32 s6, s13, 0x7fffffc0
	s_add_i32 s6, s6, 0xffff6600
	v_or_b32_e32 v144, s6, v92
	s_and_b32 s8, s23, 0x7c0
	v_lshlrev_b64 v[0:1], 13, v[144:145]
	s_waitcnt lgkmcnt(0)
	v_lshl_add_u64 v[0:1], s[30:31], 0, v[0:1]
	s_lshl_b32 s74, s8, 2
	v_lshl_add_u64 v[0:1], v[0:1], 0, s[74:75]
	v_lshlrev_b32_e32 v144, 2, v70
	v_lshl_add_u64 v[56:57], v[0:1], 0, v[144:145]
	v_add_co_u32_e32 v4, vcc, 0x8000, v56
	s_mov_b32 s0, 0x18000
	s_nop 0
	v_addc_co_u32_e32 v5, vcc, 0, v57, vcc
	v_add_co_u32_e32 v8, vcc, s47, v56
	global_load_dwordx4 v[0:3], v[56:57], off nt
	s_nop 0
	global_load_dwordx4 v[4:7], v[4:5], off nt
	v_addc_co_u32_e32 v9, vcc, 0, v57, vcc
	v_add_co_u32_e32 v12, vcc, s0, v56
	s_mov_b32 s0, 0x48000
	s_nop 0
	v_addc_co_u32_e32 v13, vcc, 0, v57, vcc
	v_add_co_u32_e32 v16, vcc, 0x20000, v56
	global_load_dwordx4 v[8:11], v[8:9], off nt
	s_nop 0
	global_load_dwordx4 v[12:15], v[12:13], off nt
	v_addc_co_u32_e32 v17, vcc, 0, v57, vcc
	v_add_co_u32_e32 v20, vcc, 0x28000, v56
	s_nop 1
	v_addc_co_u32_e32 v21, vcc, 0, v57, vcc
	v_add_co_u32_e32 v24, vcc, s3, v56
	global_load_dwordx4 v[16:19], v[16:17], off nt
	s_nop 0
	global_load_dwordx4 v[20:23], v[20:21], off nt
	v_addc_co_u32_e32 v25, vcc, 0, v57, vcc
	v_add_co_u32_e32 v28, vcc, 0x38000, v56
	s_nop 1
	v_addc_co_u32_e32 v29, vcc, 0, v57, vcc
	v_add_co_u32_e32 v32, vcc, s21, v56
	global_load_dwordx4 v[24:27], v[24:25], off nt
	s_nop 0
	global_load_dwordx4 v[28:31], v[28:29], off nt
	v_addc_co_u32_e32 v33, vcc, 0, v57, vcc
	v_add_co_u32_e32 v36, vcc, s0, v56
	s_mov_b32 s0, 0x58000
	s_nop 0
	v_addc_co_u32_e32 v37, vcc, 0, v57, vcc
	v_add_co_u32_e32 v40, vcc, s20, v56
	global_load_dwordx4 v[32:35], v[32:33], off nt
	s_nop 0
	global_load_dwordx4 v[36:39], v[36:37], off nt
	v_addc_co_u32_e32 v41, vcc, 0, v57, vcc
	v_add_co_u32_e32 v44, vcc, s0, v56
	s_mov_b32 s0, 0x68000
	s_nop 0
	v_addc_co_u32_e32 v45, vcc, 0, v57, vcc
	v_add_co_u32_e32 v48, vcc, s26, v56
	global_load_dwordx4 v[40:43], v[40:41], off nt
	s_nop 0
	global_load_dwordx4 v[44:47], v[44:45], off nt
	v_addc_co_u32_e32 v49, vcc, 0, v57, vcc
	v_add_co_u32_e32 v52, vcc, s0, v56
	s_mov_b32 s0, 0x78000
	s_nop 0
	v_addc_co_u32_e32 v53, vcc, 0, v57, vcc
	v_add_co_u32_e32 v58, vcc, s48, v56
	global_load_dwordx4 v[48:51], v[48:49], off nt
	s_nop 0
	global_load_dwordx4 v[52:55], v[52:53], off nt
	v_addc_co_u32_e32 v59, vcc, 0, v57, vcc
	v_add_co_u32_e32 v60, vcc, s0, v56
	s_nop 1
	v_addc_co_u32_e32 v61, vcc, 0, v57, vcc
	global_load_dwordx4 v[56:59], v[58:59], off nt
	s_nop 0
	global_load_dwordx4 v[60:63], v[60:61], off nt
	s_waitcnt vmcnt(15)
	ds_write2_b32 v93, v0, v1 offset1:1
	ds_write2_b32 v93, v2, v3 offset0:2 offset1:3
	v_add_u32_e32 v0, 0x410, v93
	s_waitcnt vmcnt(14)
	ds_write2_b32 v0, v4, v5 offset1:1
	v_add_u32_e32 v0, 0x418, v93
	ds_write2_b32 v0, v6, v7 offset1:1
	v_add_u32_e32 v0, 0x820, v93
	s_waitcnt vmcnt(13)
	ds_write2_b32 v0, v8, v9 offset1:1
	v_add_u32_e32 v0, 0x828, v93
	ds_write2_b32 v0, v10, v11 offset1:1
	v_add_u32_e32 v0, 0xc30, v93
	s_waitcnt vmcnt(12)
	ds_write2_b32 v0, v12, v13 offset1:1
	v_add_u32_e32 v0, 0xc38, v93
	ds_write2_b32 v0, v14, v15 offset1:1
	v_add_u32_e32 v0, 0x1040, v93
	s_waitcnt vmcnt(11)
	ds_write2_b32 v0, v16, v17 offset1:1
	v_add_u32_e32 v0, 0x1048, v93
	ds_write2_b32 v0, v18, v19 offset1:1
	v_add_u32_e32 v0, 0x1450, v93
	s_waitcnt vmcnt(10)
	ds_write2_b32 v0, v20, v21 offset1:1
	v_add_u32_e32 v0, 0x1458, v93
	ds_write2_b32 v0, v22, v23 offset1:1
	v_add_u32_e32 v0, 0x1860, v93
	s_waitcnt vmcnt(9)
	ds_write2_b32 v0, v24, v25 offset1:1
	v_add_u32_e32 v0, 0x1868, v93
	ds_write2_b32 v0, v26, v27 offset1:1
	v_add_u32_e32 v0, 0x1c70, v93
	s_waitcnt vmcnt(8)
	ds_write2_b32 v0, v28, v29 offset1:1
	v_add_u32_e32 v0, 0x1c78, v93
	ds_write2_b32 v0, v30, v31 offset1:1
	v_add_u32_e32 v0, 0x2080, v93
	s_waitcnt vmcnt(7)
	ds_write2_b32 v0, v32, v33 offset1:1
	v_add_u32_e32 v0, 0x2088, v93
	ds_write2_b32 v0, v34, v35 offset1:1
	v_add_u32_e32 v0, 0x2490, v93
	s_waitcnt vmcnt(6)
	ds_write2_b32 v0, v36, v37 offset1:1
	v_add_u32_e32 v0, 0x2498, v93
	ds_write2_b32 v0, v38, v39 offset1:1
	v_add_u32_e32 v0, 0x28a0, v93
	s_waitcnt vmcnt(5)
	ds_write2_b32 v0, v40, v41 offset1:1
	v_add_u32_e32 v0, 0x28a8, v93
	ds_write2_b32 v0, v42, v43 offset1:1
	v_add_u32_e32 v0, 0x2cb0, v93
	s_waitcnt vmcnt(4)
	ds_write2_b32 v0, v44, v45 offset1:1
	v_add_u32_e32 v0, 0x2cb8, v93
	ds_write2_b32 v0, v46, v47 offset1:1
	v_add_u32_e32 v0, 0x30c0, v93
	s_waitcnt vmcnt(3)
	ds_write2_b32 v0, v48, v49 offset1:1
	v_add_u32_e32 v0, 0x30c8, v93
	ds_write2_b32 v0, v50, v51 offset1:1
	v_add_u32_e32 v0, 0x34d0, v93
	s_waitcnt vmcnt(2)
	ds_write2_b32 v0, v52, v53 offset1:1
	v_add_u32_e32 v0, 0x34d8, v93
	ds_write2_b32 v0, v54, v55 offset1:1
	v_add_u32_e32 v0, 0x38e0, v93
	s_waitcnt vmcnt(1)
	ds_write2_b32 v0, v56, v57 offset1:1
	v_add_u32_e32 v0, 0x38e8, v93
	ds_write2_b32 v0, v58, v59 offset1:1
	v_add_u32_e32 v0, 0x3cf0, v93
	s_waitcnt vmcnt(0)
	ds_write2_b32 v0, v60, v61 offset1:1
	v_add_u32_e32 v0, 0x3cf8, v93
	ds_write2_b32 v0, v62, v63 offset1:1
	ds_read2_b32 v[4:5], v95 offset0:65 offset1:73
	ds_read2_b32 v[6:7], v95 offset1:8
	ds_read2_b32 v[8:9], v95 offset0:130 offset1:138
	ds_read2_b32 v[10:11], v95 offset0:195 offset1:203
	v_add_u32_e32 v24, 0x400, v95
	ds_read2_b32 v[12:13], v24 offset0:4 offset1:12
	ds_read2_b32 v[14:15], v24 offset0:69 offset1:77
	ds_read2_b32 v[16:17], v24 offset0:134 offset1:142
	ds_read2_b32 v[18:19], v24 offset0:199 offset1:207
	s_mov_b32 s7, s75
	s_waitcnt lgkmcnt(6)
; #define LAS __attribute__((address_space(3)))
; __device__ __forceinline__ unsigned pk2(float lo, float hi) { unsigned r; asm("v_cvt_pk_bf16_f32 %0, %1, %2" : "=v"(r) : "v"(lo), "v"(hi)); return r; }
; __device__ __forceinline__ void transpose_item(const float* W, int K, int N, bf16_t* WT, int kb, int nbd, int src0, LAS float* scr, int lane, const float* gk = nullptr) {
;     const int k0 = kb * 64;
;     const float* wp = W + (size_t)(k0 + (lane >> 4)) * N + src0 + (lane & 15) * 4;
;     f32x4 v[16];
; #pragma unroll
;     for (int i = 0; i < 16; ++i) v[i] = *(const f32x4*)(wp + (size_t)(4 * i) * N);
;     ...
;     const int c = lane & 7;
; #pragma unroll
;     for (int jj = 0; jj < 8; ++jj) {
;         const int n = (lane >> 3) + 8 * jj; const LAS float* s = scr + (8 * c) * 65 + n;
;         u32x4 o; o.x = pk2(s[0], s[65]); o.y = pk2(s[2 * 65], s[3 * 65]); o.z = pk2(s[4 * 65], s[5 * 65]); o.w = pk2(s[6 * 65], s[7 * 65]);
;         *(u32x4*)(WT + (size_t)(nbd * 64 + n) * K + k0 + 8 * c) = o;
;     }
	v_cvt_pk_bf16_f32 v0, v6, v4
	v_or_b32_e32 v4, s8, v94
	v_lshl_add_u64 v[20:21], s[6:7], 1, v[72:73]
	v_lshlrev_b32_e32 v144, 12, v4
	v_lshl_add_u64 v[22:23], v[20:21], 0, v[144:145]
	s_waitcnt lgkmcnt(4)
	v_cvt_pk_bf16_f32 v1, v8, v10
	s_waitcnt lgkmcnt(2)
	v_cvt_pk_bf16_f32 v2, v12, v14
	s_waitcnt lgkmcnt(0)
	v_cvt_pk_bf16_f32 v3, v16, v18
	global_store_dwordx4 v[22:23], v[0:3], off
	v_or_b32_e32 v4, s8, v96
	v_lshlrev_b32_e32 v144, 12, v4
	v_cvt_pk_bf16_f32 v0, v7, v5
	v_cvt_pk_bf16_f32 v1, v9, v11
	v_cvt_pk_bf16_f32 v2, v13, v15
	v_cvt_pk_bf16_f32 v3, v17, v19
	ds_read2_b32 v[6:7], v95 offset0:16 offset1:24
	ds_read2_b32 v[8:9], v95 offset0:81 offset1:89
	ds_read2_b32 v[10:11], v95 offset0:146 offset1:154
	ds_read2_b32 v[12:13], v95 offset0:211 offset1:219
	ds_read2_b32 v[14:15], v24 offset0:20 offset1:28
	ds_read2_b32 v[16:17], v24 offset0:85 offset1:93
	ds_read2_b32 v[18:19], v24 offset0:150 offset1:158
	ds_read2_b32 v[22:23], v24 offset0:215 offset1:223
	v_lshl_add_u64 v[4:5], v[20:21], 0, v[144:145]
	global_store_dwordx4 v[4:5], v[0:3], off
	v_or_b32_e32 v4, s8, v97
	v_lshlrev_b32_e32 v144, 12, v4
	v_lshl_add_u64 v[4:5], v[20:21], 0, v[144:145]
	s_waitcnt lgkmcnt(6)
	v_cvt_pk_bf16_f32 v0, v6, v8
	s_waitcnt lgkmcnt(4)
	v_cvt_pk_bf16_f32 v1, v10, v12
	s_waitcnt lgkmcnt(2)
	v_cvt_pk_bf16_f32 v2, v14, v16
	s_waitcnt lgkmcnt(0)
	v_cvt_pk_bf16_f32 v3, v18, v22
	global_store_dwordx4 v[4:5], v[0:3], off
	v_or_b32_e32 v4, s8, v98
	v_lshlrev_b32_e32 v144, 12, v4
	v_cvt_pk_bf16_f32 v0, v7, v9
	v_cvt_pk_bf16_f32 v1, v11, v13
	v_cvt_pk_bf16_f32 v2, v15, v17
	v_cvt_pk_bf16_f32 v3, v19, v23
	ds_read2_b32 v[6:7], v95 offset0:32 offset1:40
	ds_read2_b32 v[8:9], v95 offset0:97 offset1:105
	ds_read2_b32 v[10:11], v95 offset0:162 offset1:170
	ds_read2_b32 v[12:13], v95 offset0:227 offset1:235
	ds_read2_b32 v[14:15], v24 offset0:36 offset1:44
	ds_read2_b32 v[16:17], v24 offset0:101 offset1:109
	ds_read2_b32 v[18:19], v24 offset0:166 offset1:174
	ds_read2_b32 v[22:23], v24 offset0:231 offset1:239
	v_lshl_add_u64 v[4:5], v[20:21], 0, v[144:145]
	global_store_dwordx4 v[4:5], v[0:3], off
	v_or_b32_e32 v4, s8, v99
	v_lshlrev_b32_e32 v144, 12, v4
	v_lshl_add_u64 v[4:5], v[20:21], 0, v[144:145]
	s_waitcnt lgkmcnt(6)
	v_cvt_pk_bf16_f32 v0, v6, v8
	s_waitcnt lgkmcnt(4)
	v_cvt_pk_bf16_f32 v1, v10, v12
	s_waitcnt lgkmcnt(2)
	v_cvt_pk_bf16_f32 v2, v14, v16
	s_waitcnt lgkmcnt(0)
	v_cvt_pk_bf16_f32 v3, v18, v22
	global_store_dwordx4 v[4:5], v[0:3], off
	v_or_b32_e32 v4, s8, v100
	v_lshlrev_b32_e32 v144, 12, v4
	v_cvt_pk_bf16_f32 v0, v7, v9
	v_cvt_pk_bf16_f32 v1, v11, v13
	v_cvt_pk_bf16_f32 v2, v15, v17
	v_cvt_pk_bf16_f32 v3, v19, v23
	ds_read2_b32 v[6:7], v95 offset0:48 offset1:56
	ds_read2_b32 v[8:9], v95 offset0:113 offset1:121
	ds_read2_b32 v[10:11], v95 offset0:178 offset1:186
	ds_read2_b32 v[12:13], v95 offset0:243 offset1:251
	ds_read2_b32 v[14:15], v24 offset0:52 offset1:60
	ds_read2_b32 v[16:17], v24 offset0:117 offset1:125
	ds_read2_b32 v[18:19], v24 offset0:182 offset1:190
	ds_read2_b32 v[22:23], v24 offset0:247 offset1:255
	v_lshl_add_u64 v[4:5], v[20:21], 0, v[144:145]
	global_store_dwordx4 v[4:5], v[0:3], off
	v_or_b32_e32 v4, s8, v101
	v_lshlrev_b32_e32 v144, 12, v4
	v_lshl_add_u64 v[4:5], v[20:21], 0, v[144:145]
	s_waitcnt lgkmcnt(6)
	v_cvt_pk_bf16_f32 v0, v6, v8
	s_waitcnt lgkmcnt(4)
	v_cvt_pk_bf16_f32 v1, v10, v12
	s_waitcnt lgkmcnt(2)
	v_cvt_pk_bf16_f32 v2, v14, v16
	s_waitcnt lgkmcnt(0)
	v_cvt_pk_bf16_f32 v3, v18, v22
	global_store_dwordx4 v[4:5], v[0:3], off
	v_or_b32_e32 v4, s8, v102
	v_lshlrev_b32_e32 v144, 12, v4
	v_lshl_add_u64 v[4:5], v[20:21], 0, v[144:145]
	v_cvt_pk_bf16_f32 v0, v7, v9
	v_cvt_pk_bf16_f32 v1, v11, v13
	v_cvt_pk_bf16_f32 v2, v15, v17
	v_cvt_pk_bf16_f32 v3, v19, v23
	global_store_dwordx4 v[4:5], v[0:3], off
	s_mov_b64 s[6:7], 0
.LBB0_265:
	s_andn2_b64 vcc, exec, s[6:7]
	s_cbranch_vccnz .LBB0_267
	s_and_b32 s6, s19, 0x1ffc0
	s_add_i32 s6, s6, 0xfffed400
	v_or_b32_e32 v144, s6, v92
	v_readlane_b32 s80, v252, 0
	s_and_b32 s8, s23, 0x3c0
	v_lshlrev_b64 v[0:1], 12, v[144:145]
	v_readlane_b32 s86, v252, 6
	v_readlane_b32 s87, v252, 7
	s_lshl_b32 s74, s8, 2
	v_lshlrev_b32_e32 v144, 2, v70
	v_lshl_add_u64 v[0:1], s[86:87], 0, v[0:1]
	v_lshl_add_u64 v[0:1], v[0:1], 0, s[74:75]
	v_lshl_add_u64 v[56:57], v[0:1], 0, v[144:145]
	v_add_co_u32_e32 v4, vcc, 0x4000, v56
	s_mov_b32 s7, 0x38000
	s_waitcnt lgkmcnt(0)
	v_addc_co_u32_e32 v5, vcc, 0, v57, vcc
	v_add_co_u32_e32 v8, vcc, 0x8000, v56
	global_load_dwordx4 v[0:3], v[56:57], off nt
	s_nop 0
	global_load_dwordx4 v[4:7], v[4:5], off nt
	v_addc_co_u32_e32 v9, vcc, 0, v57, vcc
	v_add_co_u32_e32 v12, vcc, 0xc000, v56
	v_readlane_b32 s81, v252, 1
	s_nop 0
	v_addc_co_u32_e32 v13, vcc, 0, v57, vcc
	v_add_co_u32_e32 v16, vcc, 0x10000, v56
	global_load_dwordx4 v[8:11], v[8:9], off nt
	s_nop 0
	global_load_dwordx4 v[12:15], v[12:13], off nt
	v_addc_co_u32_e32 v17, vcc, 0, v57, vcc
	v_add_co_u32_e32 v20, vcc, 0x14000, v56
	v_readlane_b32 s82, v252, 2
	s_nop 0
	v_addc_co_u32_e32 v21, vcc, 0, v57, vcc
	v_add_co_u32_e32 v24, vcc, 0x18000, v56
	global_load_dwordx4 v[16:19], v[16:17], off nt
	s_nop 0
	global_load_dwordx4 v[20:23], v[20:21], off nt
	v_addc_co_u32_e32 v25, vcc, 0, v57, vcc
	v_add_co_u32_e32 v28, vcc, 0x1c000, v56
	v_readlane_b32 s83, v252, 3
	s_nop 0
	v_addc_co_u32_e32 v29, vcc, 0, v57, vcc
	v_add_co_u32_e32 v32, vcc, 0x20000, v56
	global_load_dwordx4 v[24:27], v[24:25], off nt
	s_nop 0
	global_load_dwordx4 v[28:31], v[28:29], off nt
	v_addc_co_u32_e32 v33, vcc, 0, v57, vcc
	v_add_co_u32_e32 v36, vcc, 0x24000, v56
	v_readlane_b32 s84, v252, 4
	s_waitcnt lgkmcnt(0)
; #define LAS __attribute__((address_space(3)))
; #define SCHED_FENCE() __builtin_amdgcn_sched_barrier(0)
; __device__ __forceinline__ void transpose_item(const float* W, int K, int N, bf16_t* WT, int kb, int nbd, int src0, LAS float* scr, int lane, const float* gk = nullptr) {
;     ...
;     const float* wp = W + (size_t)(k0 + (lane >> 4)) * N + src0 + (lane & 15) * 4;
;     f32x4 v[16];
; #pragma unroll
;     for (int i = 0; i < 16; ++i) v[i] = *(const f32x4*)(wp + (size_t)(4 * i) * N);
;     SCHED_FENCE();
; #pragma unroll
;     for (int i = 0; i < 16; ++i) { if (gk) v[i] = v[i] * gk[k0 + 4 * i + (lane >> 4)];
;         LAS float* s = scr + (4 * i + (lane >> 4)) * 65 + (lane & 15) * 4; s[0] = v[i].x; s[1] = v[i].y; s[2] = v[i].z; s[3] = v[i].w; }
	v_addc_co_u32_e32 v37, vcc, 0, v57, vcc
	v_add_co_u32_e32 v40, vcc, 0x28000, v56
	global_load_dwordx4 v[32:35], v[32:33], off nt
	s_nop 0
	global_load_dwordx4 v[36:39], v[36:37], off nt
	v_addc_co_u32_e32 v41, vcc, 0, v57, vcc
	v_add_co_u32_e32 v44, vcc, 0x2c000, v56
	v_readlane_b32 s85, v252, 5
	s_nop 0
	v_addc_co_u32_e32 v45, vcc, 0, v57, vcc
	v_add_co_u32_e32 v48, vcc, s3, v56
	global_load_dwordx4 v[40:43], v[40:41], off nt
	s_nop 0
	global_load_dwordx4 v[44:47], v[44:45], off nt
	v_addc_co_u32_e32 v49, vcc, 0, v57, vcc
	v_add_co_u32_e32 v52, vcc, 0x34000, v56
	v_readlane_b32 s88, v252, 8
	s_nop 0
	v_addc_co_u32_e32 v53, vcc, 0, v57, vcc
	v_add_co_u32_e32 v58, vcc, s7, v56
	global_load_dwordx4 v[48:51], v[48:49], off nt
	s_nop 0
	global_load_dwordx4 v[52:55], v[52:53], off nt
	v_addc_co_u32_e32 v59, vcc, 0, v57, vcc
	v_add_co_u32_e32 v60, vcc, 0x3c000, v56
	v_readlane_b32 s89, v252, 9
	s_nop 0
	v_addc_co_u32_e32 v61, vcc, 0, v57, vcc
	global_load_dwordx4 v[56:59], v[58:59], off nt
	s_nop 0
	global_load_dwordx4 v[60:63], v[60:61], off nt
	v_readlane_b32 s90, v252, 10
	v_readlane_b32 s91, v252, 11
	v_readlane_b32 s92, v252, 12
	v_readlane_b32 s93, v252, 13
	v_readlane_b32 s94, v252, 14
	v_readlane_b32 s95, v252, 15
	s_waitcnt vmcnt(15)
	ds_write2_b32 v93, v0, v1 offset1:1
	ds_write2_b32 v93, v2, v3 offset0:2 offset1:3
	v_add_u32_e32 v0, 0x410, v93
	s_waitcnt vmcnt(14)
	ds_write2_b32 v0, v4, v5 offset1:1
	v_add_u32_e32 v0, 0x418, v93
	ds_write2_b32 v0, v6, v7 offset1:1
	v_add_u32_e32 v0, 0x820, v93
	s_waitcnt vmcnt(13)
	ds_write2_b32 v0, v8, v9 offset1:1
	v_add_u32_e32 v0, 0x828, v93
	ds_write2_b32 v0, v10, v11 offset1:1
	v_add_u32_e32 v0, 0xc30, v93
	s_waitcnt vmcnt(12)
	ds_write2_b32 v0, v12, v13 offset1:1
	v_add_u32_e32 v0, 0xc38, v93
	ds_write2_b32 v0, v14, v15 offset1:1
	v_add_u32_e32 v0, 0x1040, v93
	s_waitcnt vmcnt(11)
	ds_write2_b32 v0, v16, v17 offset1:1
	v_add_u32_e32 v0, 0x1048, v93
	ds_write2_b32 v0, v18, v19 offset1:1
	v_add_u32_e32 v0, 0x1450, v93
	s_waitcnt vmcnt(10)
	ds_write2_b32 v0, v20, v21 offset1:1
	v_add_u32_e32 v0, 0x1458, v93
	ds_write2_b32 v0, v22, v23 offset1:1
	v_add_u32_e32 v0, 0x1860, v93
	s_waitcnt vmcnt(9)
	ds_write2_b32 v0, v24, v25 offset1:1
	v_add_u32_e32 v0, 0x1868, v93
	ds_write2_b32 v0, v26, v27 offset1:1
	v_add_u32_e32 v0, 0x1c70, v93
	s_waitcnt vmcnt(8)
	ds_write2_b32 v0, v28, v29 offset1:1
	v_add_u32_e32 v0, 0x1c78, v93
	ds_write2_b32 v0, v30, v31 offset1:1
	v_add_u32_e32 v0, 0x2080, v93
	s_waitcnt vmcnt(7)
	ds_write2_b32 v0, v32, v33 offset1:1
	v_add_u32_e32 v0, 0x2088, v93
	ds_write2_b32 v0, v34, v35 offset1:1
	v_add_u32_e32 v0, 0x2490, v93
	s_waitcnt vmcnt(6)
	ds_write2_b32 v0, v36, v37 offset1:1
	v_add_u32_e32 v0, 0x2498, v93
	ds_write2_b32 v0, v38, v39 offset1:1
	v_add_u32_e32 v0, 0x28a0, v93
	s_waitcnt vmcnt(5)
	ds_write2_b32 v0, v40, v41 offset1:1
	v_add_u32_e32 v0, 0x28a8, v93
	ds_write2_b32 v0, v42, v43 offset1:1
	v_add_u32_e32 v0, 0x2cb0, v93
	s_waitcnt vmcnt(4)
	ds_write2_b32 v0, v44, v45 offset1:1
	v_add_u32_e32 v0, 0x2cb8, v93
	ds_write2_b32 v0, v46, v47 offset1:1
	v_add_u32_e32 v0, 0x30c0, v93
	s_waitcnt vmcnt(3)
	ds_write2_b32 v0, v48, v49 offset1:1
	v_add_u32_e32 v0, 0x30c8, v93
	ds_write2_b32 v0, v50, v51 offset1:1
	v_add_u32_e32 v0, 0x34d0, v93
	s_waitcnt vmcnt(2)
	ds_write2_b32 v0, v52, v53 offset1:1
	v_add_u32_e32 v0, 0x34d8, v93
	ds_write2_b32 v0, v54, v55 offset1:1
	v_add_u32_e32 v0, 0x38e0, v93
	s_waitcnt vmcnt(1)
	ds_write2_b32 v0, v56, v57 offset1:1
	v_add_u32_e32 v0, 0x38e8, v93
	ds_write2_b32 v0, v58, v59 offset1:1
	v_add_u32_e32 v0, 0x3cf0, v93
	s_waitcnt vmcnt(0)
	ds_write2_b32 v0, v60, v61 offset1:1
	v_add_u32_e32 v0, 0x3cf8, v93
	ds_write2_b32 v0, v62, v63 offset1:1
	ds_read2_b32 v[4:5], v95 offset0:65 offset1:73
	ds_read2_b32 v[6:7], v95 offset1:8
	ds_read2_b32 v[8:9], v95 offset0:130 offset1:138
	ds_read2_b32 v[10:11], v95 offset0:195 offset1:203
	v_add_u32_e32 v24, 0x400, v95
	ds_read2_b32 v[12:13], v24 offset0:4 offset1:12
	ds_read2_b32 v[14:15], v24 offset0:69 offset1:77
	ds_read2_b32 v[16:17], v24 offset0:134 offset1:142
	ds_read2_b32 v[18:19], v24 offset0:199 offset1:207
	s_mov_b32 s7, s75
	s_waitcnt lgkmcnt(6)
; #define LAS __attribute__((address_space(3)))
; __device__ __forceinline__ unsigned pk2(float lo, float hi) { unsigned r; asm("v_cvt_pk_bf16_f32 %0, %1, %2" : "=v"(r) : "v"(lo), "v"(hi)); return r; }
; __device__ __forceinline__ void transpose_item(const float* W, int K, int N, bf16_t* WT, int kb, int nbd, int src0, LAS float* scr, int lane, const float* gk = nullptr) {
;     ...
;     const int c = lane & 7;
; #pragma unroll
;     for (int jj = 0; jj < 8; ++jj) {
;         const int n = (lane >> 3) + 8 * jj; const LAS float* s = scr + (8 * c) * 65 + n;
;         u32x4 o; o.x = pk2(s[0], s[65]); o.y = pk2(s[2 * 65], s[3 * 65]); o.z = pk2(s[4 * 65], s[5 * 65]); o.w = pk2(s[6 * 65], s[7 * 65]);
;         *(u32x4*)(WT + (size_t)(nbd * 64 + n) * K + k0 + 8 * c) = o;
;     }
	v_cvt_pk_bf16_f32 v0, v6, v4
	v_or_b32_e32 v4, s8, v94
	v_lshl_add_u64 v[20:21], s[6:7], 1, v[74:75]
	v_lshlrev_b32_e32 v144, 12, v4
	v_lshl_add_u64 v[22:23], v[20:21], 0, v[144:145]
	s_waitcnt lgkmcnt(4)
	v_cvt_pk_bf16_f32 v1, v8, v10
	s_waitcnt lgkmcnt(2)
	v_cvt_pk_bf16_f32 v2, v12, v14
	s_waitcnt lgkmcnt(0)
	v_cvt_pk_bf16_f32 v3, v16, v18
	global_store_dwordx4 v[22:23], v[0:3], off
	v_or_b32_e32 v4, s8, v96
	v_lshlrev_b32_e32 v144, 12, v4
	v_cvt_pk_bf16_f32 v0, v7, v5
	v_cvt_pk_bf16_f32 v1, v9, v11
	v_cvt_pk_bf16_f32 v2, v13, v15
	v_cvt_pk_bf16_f32 v3, v17, v19
	ds_read2_b32 v[6:7], v95 offset0:16 offset1:24
	ds_read2_b32 v[8:9], v95 offset0:81 offset1:89
	ds_read2_b32 v[10:11], v95 offset0:146 offset1:154
	ds_read2_b32 v[12:13], v95 offset0:211 offset1:219
	ds_read2_b32 v[14:15], v24 offset0:20 offset1:28
	ds_read2_b32 v[16:17], v24 offset0:85 offset1:93
	ds_read2_b32 v[18:19], v24 offset0:150 offset1:158
	ds_read2_b32 v[22:23], v24 offset0:215 offset1:223
	v_lshl_add_u64 v[4:5], v[20:21], 0, v[144:145]
	global_store_dwordx4 v[4:5], v[0:3], off
	v_or_b32_e32 v4, s8, v97
	v_lshlrev_b32_e32 v144, 12, v4
	v_lshl_add_u64 v[4:5], v[20:21], 0, v[144:145]
	s_waitcnt lgkmcnt(6)
	v_cvt_pk_bf16_f32 v0, v6, v8
	s_waitcnt lgkmcnt(4)
	v_cvt_pk_bf16_f32 v1, v10, v12
	s_waitcnt lgkmcnt(2)
	v_cvt_pk_bf16_f32 v2, v14, v16
	s_waitcnt lgkmcnt(0)
	v_cvt_pk_bf16_f32 v3, v18, v22
	global_store_dwordx4 v[4:5], v[0:3], off
	v_or_b32_e32 v4, s8, v98
	v_lshlrev_b32_e32 v144, 12, v4
	v_cvt_pk_bf16_f32 v0, v7, v9
	v_cvt_pk_bf16_f32 v1, v11, v13
	v_cvt_pk_bf16_f32 v2, v15, v17
	v_cvt_pk_bf16_f32 v3, v19, v23
	ds_read2_b32 v[6:7], v95 offset0:32 offset1:40
	ds_read2_b32 v[8:9], v95 offset0:97 offset1:105
	ds_read2_b32 v[10:11], v95 offset0:162 offset1:170
	ds_read2_b32 v[12:13], v95 offset0:227 offset1:235
	ds_read2_b32 v[14:15], v24 offset0:36 offset1:44
	ds_read2_b32 v[16:17], v24 offset0:101 offset1:109
	ds_read2_b32 v[18:19], v24 offset0:166 offset1:174
	ds_read2_b32 v[22:23], v24 offset0:231 offset1:239
	v_lshl_add_u64 v[4:5], v[20:21], 0, v[144:145]
	global_store_dwordx4 v[4:5], v[0:3], off
	v_or_b32_e32 v4, s8, v99
	v_lshlrev_b32_e32 v144, 12, v4
	v_lshl_add_u64 v[4:5], v[20:21], 0, v[144:145]
	s_waitcnt lgkmcnt(6)
	v_cvt_pk_bf16_f32 v0, v6, v8
	s_waitcnt lgkmcnt(4)
	v_cvt_pk_bf16_f32 v1, v10, v12
	s_waitcnt lgkmcnt(2)
	v_cvt_pk_bf16_f32 v2, v14, v16
	s_waitcnt lgkmcnt(0)
	v_cvt_pk_bf16_f32 v3, v18, v22
	global_store_dwordx4 v[4:5], v[0:3], off
	v_or_b32_e32 v4, s8, v100
	v_lshlrev_b32_e32 v144, 12, v4
	v_cvt_pk_bf16_f32 v0, v7, v9
	v_cvt_pk_bf16_f32 v1, v11, v13
	v_cvt_pk_bf16_f32 v2, v15, v17
	v_cvt_pk_bf16_f32 v3, v19, v23
	ds_read2_b32 v[6:7], v95 offset0:48 offset1:56
	ds_read2_b32 v[8:9], v95 offset0:113 offset1:121
	ds_read2_b32 v[10:11], v95 offset0:178 offset1:186
	ds_read2_b32 v[12:13], v95 offset0:243 offset1:251
	ds_read2_b32 v[14:15], v24 offset0:52 offset1:60
	ds_read2_b32 v[16:17], v24 offset0:117 offset1:125
	ds_read2_b32 v[18:19], v24 offset0:182 offset1:190
	ds_read2_b32 v[22:23], v24 offset0:247 offset1:255
	v_lshl_add_u64 v[4:5], v[20:21], 0, v[144:145]
	global_store_dwordx4 v[4:5], v[0:3], off
	v_or_b32_e32 v4, s8, v101
	v_lshlrev_b32_e32 v144, 12, v4
	v_lshl_add_u64 v[4:5], v[20:21], 0, v[144:145]
	s_waitcnt lgkmcnt(6)
	v_cvt_pk_bf16_f32 v0, v6, v8
	s_waitcnt lgkmcnt(4)
	v_cvt_pk_bf16_f32 v1, v10, v12
	s_waitcnt lgkmcnt(2)
	v_cvt_pk_bf16_f32 v2, v14, v16
	s_waitcnt lgkmcnt(0)
	v_cvt_pk_bf16_f32 v3, v18, v22
	global_store_dwordx4 v[4:5], v[0:3], off
	v_or_b32_e32 v4, s8, v102
	v_lshlrev_b32_e32 v144, 12, v4
	v_lshl_add_u64 v[4:5], v[20:21], 0, v[144:145]
	v_cvt_pk_bf16_f32 v0, v7, v9
	v_cvt_pk_bf16_f32 v1, v11, v13
	v_cvt_pk_bf16_f32 v2, v15, v17
	v_cvt_pk_bf16_f32 v3, v19, v23
	global_store_dwordx4 v[4:5], v[0:3], off

; #define SCHED_FENCE() __builtin_amdgcn_sched_barrier(0)
; __device__ __forceinline__ void transpose_item(const float* W, int K, int N, bf16_t* WT, int kb, int nbd, int src0, LAS float* scr, int lane, const float* gk = nullptr) {
;     ...
;     const float* wp = W + (size_t)(k0 + (lane >> 4)) * N + src0 + (lane & 15) * 4;
;     f32x4 v[16];
; #pragma unroll
;     for (int i = 0; i < 16; ++i) v[i] = *(const f32x4*)(wp + (size_t)(4 * i) * N);
;     SCHED_FENCE();
; #pragma unroll
;     for (int i = 0; i < 16; ++i) { if (gk) v[i] = v[i] * gk[k0 + 4 * i + (lane >> 4)];
; __global__ void __launch_bounds__(512, 2) fwd_kernel(Args a) {
;     ...
;                 if (r < I_IN) { const int nb = r % 72; transpose_item(P.in[8], DM, 4608, (bf16_t*)(ws + WS_WIN), r / 72, nb, map_win(nb), scr, lane, P.in[6]); continue; } r -= I_IN;
.LBB0_278:
	s_lshl_b32 s8, s7, 6
	v_readlane_b32 s80, v252, 0
	s_and_b32 s7, s8, 0xffc0
	v_readlane_b32 s84, v252, 4
	v_readlane_b32 s85, v252, 5
	v_or_b32_e32 v64, s7, v92
	s_movk_i32 s7, 0x4800
	v_mov_b64_e32 v[0:1], s[84:85]
	v_mad_u64_u32 v[0:1], s[30:31], v64, s7, v[0:1]
	s_ashr_i32 s7, s6, 31
	v_lshl_add_u64 v[0:1], s[6:7], 2, v[0:1]
	v_lshlrev_b32_e32 v144, 2, v70
	v_lshl_add_u64 v[0:1], v[0:1], 0, v[144:145]
	v_add_co_u32_e32 v2, vcc, 0x12000, v0
	s_mov_b32 s0, 0x90000
	s_nop 0
	v_addc_co_u32_e32 v3, vcc, 0, v1, vcc
	global_load_dwordx4 v[56:59], v[0:1], off nt
	global_load_dwordx4 v[60:63], v[2:3], off nt
	v_add_co_u32_e32 v2, vcc, 0x24000, v0
	v_readlane_b32 s81, v252, 1
	s_nop 0
	v_addc_co_u32_e32 v3, vcc, 0, v1, vcc
	v_add_co_u32_e32 v4, vcc, 0x36000, v0
	v_readlane_b32 s82, v252, 2
	s_waitcnt lgkmcnt(0)
	v_addc_co_u32_e32 v5, vcc, 0, v1, vcc
	global_load_dwordx4 v[48:51], v[2:3], off nt
	global_load_dwordx4 v[52:55], v[4:5], off nt
	v_add_co_u32_e32 v2, vcc, 0x48000, v0
	v_readlane_b32 s83, v252, 3
	s_nop 0
	v_addc_co_u32_e32 v3, vcc, 0, v1, vcc
	v_add_co_u32_e32 v4, vcc, 0x5a000, v0
	v_readlane_b32 s86, v252, 6
	s_nop 0
	v_addc_co_u32_e32 v5, vcc, 0, v1, vcc
	global_load_dwordx4 v[40:43], v[2:3], off nt
	global_load_dwordx4 v[44:47], v[4:5], off nt
	v_add_co_u32_e32 v2, vcc, 0x6c000, v0
	v_readlane_b32 s87, v252, 7
	s_nop 0
	v_addc_co_u32_e32 v3, vcc, 0, v1, vcc
	v_add_co_u32_e32 v4, vcc, 0x7e000, v0
	v_readlane_b32 s88, v252, 8
	s_nop 0
	v_addc_co_u32_e32 v5, vcc, 0, v1, vcc
	global_load_dwordx4 v[32:35], v[2:3], off nt
	s_waitcnt lgkmcnt(0)
	global_load_dwordx4 v[36:39], v[4:5], off nt
	v_add_co_u32_e32 v2, vcc, s0, v0
	v_readlane_b32 s89, v252, 9
	s_nop 0
	v_addc_co_u32_e32 v3, vcc, 0, v1, vcc
	v_add_co_u32_e32 v4, vcc, 0xa2000, v0
	v_readlane_b32 s90, v252, 10
	s_nop 0
	v_addc_co_u32_e32 v5, vcc, 0, v1, vcc
	global_load_dwordx4 v[24:27], v[2:3], off nt
	global_load_dwordx4 v[28:31], v[4:5], off nt
	v_add_co_u32_e32 v2, vcc, 0xb4000, v0
	v_readlane_b32 s91, v252, 11
	s_nop 0
	v_addc_co_u32_e32 v3, vcc, 0, v1, vcc
	v_add_co_u32_e32 v4, vcc, 0xc6000, v0
	v_readlane_b32 s92, v252, 12
	s_nop 0
	v_addc_co_u32_e32 v5, vcc, 0, v1, vcc
	global_load_dwordx4 v[16:19], v[2:3], off nt
	global_load_dwordx4 v[20:23], v[4:5], off nt
	v_add_co_u32_e32 v2, vcc, 0xd8000, v0
	v_readlane_b32 s93, v252, 13
	s_nop 0
	v_addc_co_u32_e32 v3, vcc, 0, v1, vcc
	v_add_co_u32_e32 v4, vcc, 0xea000, v0
	v_readlane_b32 s94, v252, 14
	s_nop 0
	v_addc_co_u32_e32 v5, vcc, 0, v1, vcc
	global_load_dwordx4 v[8:11], v[2:3], off nt
	global_load_dwordx4 v[12:15], v[4:5], off nt
	v_add_co_u32_e32 v2, vcc, 0xfc000, v0
	v_readlane_b32 s95, v252, 15
	s_nop 0
	v_addc_co_u32_e32 v3, vcc, 0, v1, vcc
	v_add_co_u32_e32 v4, vcc, 0x10e000, v0
	s_nop 1
	v_addc_co_u32_e32 v5, vcc, 0, v1, vcc
	global_load_dwordx4 v[0:3], v[2:3], off nt
	s_nop 0
	global_load_dwordx4 v[4:7], v[4:5], off nt
	v_readlane_b32 s0, v251, 20
	v_readlane_b32 s1, v251, 21
	s_andn2_b64 vcc, exec, s[0:1]
	v_lshlrev_b32_e32 v90, 2, v64
	v_cndmask_b32_e64 v65, 0, 1, s[0:1]
	v_cmp_ne_u32_e64 s[38:39], 1, v65
	s_cbranch_vccnz .LBB0_378
	global_load_dword v64, v90, s[80:81]
	global_load_dword v104, v90, s[80:81] offset:16
	s_waitcnt vmcnt(1)
	v_pk_mul_f32 v[86:87], v[58:59], v[64:65] op_sel_hi:[1,0]
	v_pk_mul_f32 v[88:89], v[56:57], v[64:65] op_sel_hi:[1,0]
	s_waitcnt vmcnt(0)
	v_pk_mul_f32 v[66:67], v[62:63], v[104:105] op_sel_hi:[1,0]
	v_pk_mul_f32 v[64:65], v[60:61], v[104:105] op_sel_hi:[1,0]
	s_cbranch_execnz .LBB0_281

; #define LAS __attribute__((address_space(3)))
; #define SCHED_FENCE() __builtin_amdgcn_sched_barrier(0)
; __device__ __forceinline__ void transpose_item(const float* W, int K, int N, bf16_t* WT, int kb, int nbd, int src0, LAS float* scr, int lane, const float* gk = nullptr) {
;     ...
;     const float* wp = W + (size_t)(k0 + (lane >> 4)) * N + src0 + (lane & 15) * 4;
;     f32x4 v[16];
; #pragma unroll
;     for (int i = 0; i < 16; ++i) v[i] = *(const f32x4*)(wp + (size_t)(4 * i) * N);
;     SCHED_FENCE();
; #pragma unroll
;     for (int i = 0; i < 16; ++i) { if (gk) v[i] = v[i] * gk[k0 + 4 * i + (lane >> 4)];
;         LAS float* s = scr + (4 * i + (lane >> 4)) * 65 + (lane & 15) * 4; s[0] = v[i].x; s[1] = v[i].y; s[2] = v[i].z; s[3] = v[i].w; }
; __global__ void __launch_bounds__(512, 2) fwd_kernel(Args a) {
;     ...
;                 if (r < I_D) { const int nb = r % 32; transpose_item(P.in[22], DFF, DM, (bf16_t*)(ws + WS_WD2), r / 32, nb, nb * 64, scr, lane); continue; } r -= I_D;
.LBB0_304:
	s_andn2_b64 vcc, exec, s[6:7]
	s_cbranch_vccnz .LBB0_306
	s_load_dwordx2 s[30:31], s[40:41], 0xb0
	s_and_b32 s6, s13, 0xffc0
	s_addk_i32 s6, 0x9200
	v_or_b32_e32 v144, s6, v92
	s_and_b32 s8, s23, 0x7c0
	v_lshlrev_b64 v[0:1], 13, v[144:145]
	s_waitcnt lgkmcnt(0)
	v_lshl_add_u64 v[0:1], s[30:31], 0, v[0:1]
	s_lshl_b32 s74, s8, 2
	v_lshl_add_u64 v[0:1], v[0:1], 0, s[74:75]
	v_lshlrev_b32_e32 v144, 2, v70
	v_lshl_add_u64 v[56:57], v[0:1], 0, v[144:145]
	v_add_co_u32_e32 v4, vcc, 0x8000, v56
	s_mov_b32 s0, 0x18000
	s_nop 0
	v_addc_co_u32_e32 v5, vcc, 0, v57, vcc
	v_add_co_u32_e32 v8, vcc, s47, v56
	global_load_dwordx4 v[0:3], v[56:57], off nt
	s_nop 0
	global_load_dwordx4 v[4:7], v[4:5], off nt
	v_addc_co_u32_e32 v9, vcc, 0, v57, vcc
	v_add_co_u32_e32 v12, vcc, s0, v56
	s_mov_b32 s0, 0x48000
	s_nop 0
	v_addc_co_u32_e32 v13, vcc, 0, v57, vcc
	v_add_co_u32_e32 v16, vcc, 0x20000, v56
	global_load_dwordx4 v[8:11], v[8:9], off nt
	s_nop 0
	global_load_dwordx4 v[12:15], v[12:13], off nt
	v_addc_co_u32_e32 v17, vcc, 0, v57, vcc
	v_add_co_u32_e32 v20, vcc, 0x28000, v56
	s_nop 1
	v_addc_co_u32_e32 v21, vcc, 0, v57, vcc
	v_add_co_u32_e32 v24, vcc, s3, v56
	global_load_dwordx4 v[16:19], v[16:17], off nt
	s_nop 0
	global_load_dwordx4 v[20:23], v[20:21], off nt
	v_addc_co_u32_e32 v25, vcc, 0, v57, vcc
	v_add_co_u32_e32 v28, vcc, 0x38000, v56
	s_nop 1
	v_addc_co_u32_e32 v29, vcc, 0, v57, vcc
	v_add_co_u32_e32 v32, vcc, s21, v56
	global_load_dwordx4 v[24:27], v[24:25], off nt
	s_nop 0
	global_load_dwordx4 v[28:31], v[28:29], off nt
	v_addc_co_u32_e32 v33, vcc, 0, v57, vcc
	v_add_co_u32_e32 v36, vcc, s0, v56
	s_mov_b32 s0, 0x58000
	s_nop 0
	v_addc_co_u32_e32 v37, vcc, 0, v57, vcc
	v_add_co_u32_e32 v40, vcc, s20, v56
	global_load_dwordx4 v[32:35], v[32:33], off nt
	s_nop 0
	global_load_dwordx4 v[36:39], v[36:37], off nt
	v_addc_co_u32_e32 v41, vcc, 0, v57, vcc
	v_add_co_u32_e32 v44, vcc, s0, v56
	s_mov_b32 s0, 0x68000
	s_nop 0
	v_addc_co_u32_e32 v45, vcc, 0, v57, vcc
	v_add_co_u32_e32 v48, vcc, s26, v56
	global_load_dwordx4 v[40:43], v[40:41], off nt
	s_nop 0
	global_load_dwordx4 v[44:47], v[44:45], off nt
	v_addc_co_u32_e32 v49, vcc, 0, v57, vcc
	v_add_co_u32_e32 v52, vcc, s0, v56
	s_mov_b32 s0, 0x78000
	s_nop 0
	v_addc_co_u32_e32 v53, vcc, 0, v57, vcc
	v_add_co_u32_e32 v58, vcc, s48, v56
	global_load_dwordx4 v[48:51], v[48:49], off nt
	s_nop 0
	global_load_dwordx4 v[52:55], v[52:53], off nt
	v_addc_co_u32_e32 v59, vcc, 0, v57, vcc
	v_add_co_u32_e32 v60, vcc, s0, v56
	s_nop 1
	v_addc_co_u32_e32 v61, vcc, 0, v57, vcc
	global_load_dwordx4 v[56:59], v[58:59], off nt
	s_nop 0
	global_load_dwordx4 v[60:63], v[60:61], off nt
	s_waitcnt vmcnt(15)
	ds_write2_b32 v93, v0, v1 offset1:1
	ds_write2_b32 v93, v2, v3 offset0:2 offset1:3
	v_add_u32_e32 v0, 0x410, v93
	s_waitcnt vmcnt(14)
	ds_write2_b32 v0, v4, v5 offset1:1
	v_add_u32_e32 v0, 0x418, v93
	ds_write2_b32 v0, v6, v7 offset1:1
	v_add_u32_e32 v0, 0x820, v93
	s_waitcnt vmcnt(13)
	ds_write2_b32 v0, v8, v9 offset1:1
	v_add_u32_e32 v0, 0x828, v93
	ds_write2_b32 v0, v10, v11 offset1:1
	v_add_u32_e32 v0, 0xc30, v93
	s_waitcnt vmcnt(12)
	ds_write2_b32 v0, v12, v13 offset1:1
	v_add_u32_e32 v0, 0xc38, v93
	ds_write2_b32 v0, v14, v15 offset1:1
	v_add_u32_e32 v0, 0x1040, v93
	s_waitcnt vmcnt(11)
	ds_write2_b32 v0, v16, v17 offset1:1
	v_add_u32_e32 v0, 0x1048, v93
	ds_write2_b32 v0, v18, v19 offset1:1
	v_add_u32_e32 v0, 0x1450, v93
	s_waitcnt vmcnt(10)
	ds_write2_b32 v0, v20, v21 offset1:1
	v_add_u32_e32 v0, 0x1458, v93
	ds_write2_b32 v0, v22, v23 offset1:1
	v_add_u32_e32 v0, 0x1860, v93
	s_waitcnt vmcnt(9)
	ds_write2_b32 v0, v24, v25 offset1:1
	v_add_u32_e32 v0, 0x1868, v93
	ds_write2_b32 v0, v26, v27 offset1:1
	v_add_u32_e32 v0, 0x1c70, v93
	s_waitcnt vmcnt(8)
	ds_write2_b32 v0, v28, v29 offset1:1
	v_add_u32_e32 v0, 0x1c78, v93
	ds_write2_b32 v0, v30, v31 offset1:1
	v_add_u32_e32 v0, 0x2080, v93
	s_waitcnt vmcnt(7)
	ds_write2_b32 v0, v32, v33 offset1:1
	v_add_u32_e32 v0, 0x2088, v93
	ds_write2_b32 v0, v34, v35 offset1:1
	v_add_u32_e32 v0, 0x2490, v93
	s_waitcnt vmcnt(6)
	ds_write2_b32 v0, v36, v37 offset1:1
	v_add_u32_e32 v0, 0x2498, v93
	ds_write2_b32 v0, v38, v39 offset1:1
	v_add_u32_e32 v0, 0x28a0, v93
	s_waitcnt vmcnt(5)
	ds_write2_b32 v0, v40, v41 offset1:1
	v_add_u32_e32 v0, 0x28a8, v93
	ds_write2_b32 v0, v42, v43 offset1:1
	v_add_u32_e32 v0, 0x2cb0, v93
	s_waitcnt vmcnt(4)
	ds_write2_b32 v0, v44, v45 offset1:1
	v_add_u32_e32 v0, 0x2cb8, v93
	ds_write2_b32 v0, v46, v47 offset1:1
	v_add_u32_e32 v0, 0x30c0, v93
	s_waitcnt vmcnt(3)
	ds_write2_b32 v0, v48, v49 offset1:1
	v_add_u32_e32 v0, 0x30c8, v93
	ds_write2_b32 v0, v50, v51 offset1:1
	v_add_u32_e32 v0, 0x34d0, v93
	s_waitcnt vmcnt(2)
	ds_write2_b32 v0, v52, v53 offset1:1
	v_add_u32_e32 v0, 0x34d8, v93
	ds_write2_b32 v0, v54, v55 offset1:1
	v_add_u32_e32 v0, 0x38e0, v93
	s_waitcnt vmcnt(1)
; #define LAS __attribute__((address_space(3)))
; __device__ __forceinline__ unsigned pk2(float lo, float hi) { unsigned r; asm("v_cvt_pk_bf16_f32 %0, %1, %2" : "=v"(r) : "v"(lo), "v"(hi)); return r; }
; __device__ __forceinline__ void transpose_item(const float* W, int K, int N, bf16_t* WT, int kb, int nbd, int src0, LAS float* scr, int lane, const float* gk = nullptr) {
;     ...
;         LAS float* s = scr + (4 * i + (lane >> 4)) * 65 + (lane & 15) * 4; s[0] = v[i].x; s[1] = v[i].y; s[2] = v[i].z; s[3] = v[i].w; }
;     const int c = lane & 7;
; #pragma unroll
;     for (int jj = 0; jj < 8; ++jj) {
;         const int n = (lane >> 3) + 8 * jj; const LAS float* s = scr + (8 * c) * 65 + n;
;         u32x4 o; o.x = pk2(s[0], s[65]); o.y = pk2(s[2 * 65], s[3 * 65]); o.z = pk2(s[4 * 65], s[5 * 65]); o.w = pk2(s[6 * 65], s[7 * 65]);
;         *(u32x4*)(WT + (size_t)(nbd * 64 + n) * K + k0 + 8 * c) = o;
;     }
	ds_write2_b32 v0, v56, v57 offset1:1
	v_add_u32_e32 v0, 0x38e8, v93
	ds_write2_b32 v0, v58, v59 offset1:1
	v_add_u32_e32 v0, 0x3cf0, v93
	s_waitcnt vmcnt(0)
	ds_write2_b32 v0, v60, v61 offset1:1
	v_add_u32_e32 v0, 0x3cf8, v93
	ds_write2_b32 v0, v62, v63 offset1:1
	ds_read2_b32 v[4:5], v95 offset0:65 offset1:73
	ds_read2_b32 v[6:7], v95 offset1:8
	ds_read2_b32 v[8:9], v95 offset0:130 offset1:138
	ds_read2_b32 v[10:11], v95 offset0:195 offset1:203
	v_add_u32_e32 v24, 0x400, v95
	ds_read2_b32 v[12:13], v24 offset0:4 offset1:12
	ds_read2_b32 v[14:15], v24 offset0:69 offset1:77
	ds_read2_b32 v[16:17], v24 offset0:134 offset1:142
	ds_read2_b32 v[18:19], v24 offset0:199 offset1:207
	s_waitcnt lgkmcnt(6)
	v_cvt_pk_bf16_f32 v0, v6, v4
	v_or_b32_e32 v4, s8, v94
	s_mov_b32 s7, s75
	v_mul_u32_u24_e32 v4, 0x1600, v4
	v_lshl_add_u64 v[20:21], s[6:7], 1, v[78:79]
	v_lshlrev_b32_e32 v144, 1, v4
	v_or_b32_e32 v4, s8, v96
	v_lshl_add_u64 v[22:23], v[20:21], 0, v[144:145]
	v_mul_u32_u24_e32 v4, 0x1600, v4
	s_waitcnt lgkmcnt(4)
	v_cvt_pk_bf16_f32 v1, v8, v10
	s_waitcnt lgkmcnt(2)
	v_cvt_pk_bf16_f32 v2, v12, v14
	s_waitcnt lgkmcnt(0)
	v_cvt_pk_bf16_f32 v3, v16, v18
	global_store_dwordx4 v[22:23], v[0:3], off
	v_lshlrev_b32_e32 v144, 1, v4
	s_nop 0
	v_cvt_pk_bf16_f32 v0, v7, v5
	v_cvt_pk_bf16_f32 v1, v9, v11
	v_cvt_pk_bf16_f32 v2, v13, v15
	v_cvt_pk_bf16_f32 v3, v17, v19
	v_lshl_add_u64 v[4:5], v[20:21], 0, v[144:145]
	ds_read2_b32 v[6:7], v95 offset0:16 offset1:24
	ds_read2_b32 v[8:9], v95 offset0:81 offset1:89
	ds_read2_b32 v[10:11], v95 offset0:146 offset1:154
	ds_read2_b32 v[12:13], v95 offset0:211 offset1:219
	ds_read2_b32 v[14:15], v24 offset0:20 offset1:28
	ds_read2_b32 v[16:17], v24 offset0:85 offset1:93
	ds_read2_b32 v[18:19], v24 offset0:150 offset1:158
	ds_read2_b32 v[22:23], v24 offset0:215 offset1:223
	global_store_dwordx4 v[4:5], v[0:3], off
	v_or_b32_e32 v4, s8, v97
	v_mul_u32_u24_e32 v4, 0x1600, v4
	v_lshlrev_b32_e32 v144, 1, v4
	v_lshl_add_u64 v[4:5], v[20:21], 0, v[144:145]
	s_waitcnt lgkmcnt(6)
	v_cvt_pk_bf16_f32 v0, v6, v8
	s_waitcnt lgkmcnt(4)
	v_cvt_pk_bf16_f32 v1, v10, v12
	s_waitcnt lgkmcnt(2)
	v_cvt_pk_bf16_f32 v2, v14, v16
	s_waitcnt lgkmcnt(0)
	v_cvt_pk_bf16_f32 v3, v18, v22
	global_store_dwordx4 v[4:5], v[0:3], off
	v_or_b32_e32 v4, s8, v98
	v_mul_u32_u24_e32 v4, 0x1600, v4
	v_lshlrev_b32_e32 v144, 1, v4
	v_cvt_pk_bf16_f32 v0, v7, v9
	v_cvt_pk_bf16_f32 v1, v11, v13
	v_cvt_pk_bf16_f32 v2, v15, v17
	v_cvt_pk_bf16_f32 v3, v19, v23
	v_lshl_add_u64 v[4:5], v[20:21], 0, v[144:145]
	ds_read2_b32 v[6:7], v95 offset0:32 offset1:40
	ds_read2_b32 v[8:9], v95 offset0:97 offset1:105
	ds_read2_b32 v[10:11], v95 offset0:162 offset1:170
	ds_read2_b32 v[12:13], v95 offset0:227 offset1:235
	ds_read2_b32 v[14:15], v24 offset0:36 offset1:44
	ds_read2_b32 v[16:17], v24 offset0:101 offset1:109
	ds_read2_b32 v[18:19], v24 offset0:166 offset1:174
	ds_read2_b32 v[22:23], v24 offset0:231 offset1:239
	global_store_dwordx4 v[4:5], v[0:3], off
	v_or_b32_e32 v4, s8, v99
	v_mul_u32_u24_e32 v4, 0x1600, v4
	v_lshlrev_b32_e32 v144, 1, v4
	v_lshl_add_u64 v[4:5], v[20:21], 0, v[144:145]
	s_waitcnt lgkmcnt(6)
	v_cvt_pk_bf16_f32 v0, v6, v8
	s_waitcnt lgkmcnt(4)
	v_cvt_pk_bf16_f32 v1, v10, v12
	s_waitcnt lgkmcnt(2)
	v_cvt_pk_bf16_f32 v2, v14, v16
	s_waitcnt lgkmcnt(0)
	v_cvt_pk_bf16_f32 v3, v18, v22
	global_store_dwordx4 v[4:5], v[0:3], off
	v_or_b32_e32 v4, s8, v100
	v_mul_u32_u24_e32 v4, 0x1600, v4
	v_lshlrev_b32_e32 v144, 1, v4
	v_cvt_pk_bf16_f32 v0, v7, v9
	v_cvt_pk_bf16_f32 v1, v11, v13
	v_cvt_pk_bf16_f32 v2, v15, v17
	v_cvt_pk_bf16_f32 v3, v19, v23
	v_lshl_add_u64 v[4:5], v[20:21], 0, v[144:145]
	ds_read2_b32 v[6:7], v95 offset0:48 offset1:56
	ds_read2_b32 v[8:9], v95 offset0:113 offset1:121
	ds_read2_b32 v[10:11], v95 offset0:178 offset1:186
	ds_read2_b32 v[12:13], v95 offset0:243 offset1:251
	ds_read2_b32 v[14:15], v24 offset0:52 offset1:60
	ds_read2_b32 v[16:17], v24 offset0:117 offset1:125
	ds_read2_b32 v[18:19], v24 offset0:182 offset1:190
	ds_read2_b32 v[22:23], v24 offset0:247 offset1:255
	global_store_dwordx4 v[4:5], v[0:3], off
	v_or_b32_e32 v4, s8, v101
	v_mul_u32_u24_e32 v4, 0x1600, v4
	v_lshlrev_b32_e32 v144, 1, v4
	v_lshl_add_u64 v[4:5], v[20:21], 0, v[144:145]
	s_waitcnt lgkmcnt(6)
	v_cvt_pk_bf16_f32 v0, v6, v8
	s_waitcnt lgkmcnt(4)
	v_cvt_pk_bf16_f32 v1, v10, v12
	s_waitcnt lgkmcnt(2)
	v_cvt_pk_bf16_f32 v2, v14, v16
	s_waitcnt lgkmcnt(0)
	v_cvt_pk_bf16_f32 v3, v18, v22
	global_store_dwordx4 v[4:5], v[0:3], off
	v_or_b32_e32 v4, s8, v102
	v_mul_u32_u24_e32 v4, 0x1600, v4
	v_lshlrev_b32_e32 v144, 1, v4
	v_lshl_add_u64 v[4:5], v[20:21], 0, v[144:145]
	v_cvt_pk_bf16_f32 v0, v7, v9
	v_cvt_pk_bf16_f32 v1, v11, v13
	v_cvt_pk_bf16_f32 v2, v15, v17
	v_cvt_pk_bf16_f32 v3, v19, v23
	global_store_dwordx4 v[4:5], v[0:3], off

; #define LAS __attribute__((address_space(3)))
; #define SCHED_FENCE() __builtin_amdgcn_sched_barrier(0)
; __device__ __forceinline__ void transpose_item(const float* W, int K, int N, bf16_t* WT, int kb, int nbd, int src0, LAS float* scr, int lane, const float* gk = nullptr) {
;     ...
;     const float* wp = W + (size_t)(k0 + (lane >> 4)) * N + src0 + (lane & 15) * 4;
;     f32x4 v[16];
; #pragma unroll
;     for (int i = 0; i < 16; ++i) v[i] = *(const f32x4*)(wp + (size_t)(4 * i) * N);
;     SCHED_FENCE();
; #pragma unroll
;     for (int i = 0; i < 16; ++i) { if (gk) v[i] = v[i] * gk[k0 + 4 * i + (lane >> 4)];
;         LAS float* s = scr + (4 * i + (lane >> 4)) * 65 + (lane & 15) * 4; s[0] = v[i].x; s[1] = v[i].y; s[2] = v[i].z; s[3] = v[i].w; }
; __global__ void __launch_bounds__(512, 2) fwd_kernel(Args a) {
;     ...
;                 if (r < I_D) { const int nb = r % 32; transpose_item(P.in[4], DFF, DM, (bf16_t*)(ws + WS_WD1), r / 32, nb, nb * 64, scr, lane); continue; } r -= I_D;
.LBB0_307:
	s_andn2_b64 vcc, exec, s[6:7]
	s_cbranch_vccnz .LBB0_309
	s_load_dwordx2 s[30:31], s[40:41], 0x20
	s_and_b32 s6, s13, 0x7fc0
	s_addk_i32 s6, 0xa800
	v_or_b32_e32 v144, s6, v92
	s_and_b32 s8, s23, 0x7c0
	v_lshlrev_b64 v[0:1], 13, v[144:145]
	s_waitcnt lgkmcnt(0)
	v_lshl_add_u64 v[0:1], s[30:31], 0, v[0:1]
	s_lshl_b32 s74, s8, 2
	v_lshl_add_u64 v[0:1], v[0:1], 0, s[74:75]
	v_lshlrev_b32_e32 v144, 2, v70
	v_lshl_add_u64 v[56:57], v[0:1], 0, v[144:145]
	v_add_co_u32_e32 v4, vcc, 0x8000, v56
	s_mov_b32 s0, 0x18000
	s_nop 0
	v_addc_co_u32_e32 v5, vcc, 0, v57, vcc
	v_add_co_u32_e32 v8, vcc, s47, v56
	global_load_dwordx4 v[0:3], v[56:57], off nt
	s_nop 0
	global_load_dwordx4 v[4:7], v[4:5], off nt
	v_addc_co_u32_e32 v9, vcc, 0, v57, vcc
	v_add_co_u32_e32 v12, vcc, s0, v56
	s_mov_b32 s0, 0x48000
	s_nop 0
	v_addc_co_u32_e32 v13, vcc, 0, v57, vcc
	v_add_co_u32_e32 v16, vcc, 0x20000, v56
	global_load_dwordx4 v[8:11], v[8:9], off nt
	s_nop 0
	global_load_dwordx4 v[12:15], v[12:13], off nt
	v_addc_co_u32_e32 v17, vcc, 0, v57, vcc
	v_add_co_u32_e32 v20, vcc, 0x28000, v56
	s_nop 1
	v_addc_co_u32_e32 v21, vcc, 0, v57, vcc
	v_add_co_u32_e32 v24, vcc, s3, v56
	global_load_dwordx4 v[16:19], v[16:17], off nt
	s_nop 0
	global_load_dwordx4 v[20:23], v[20:21], off nt
	v_addc_co_u32_e32 v25, vcc, 0, v57, vcc
	v_add_co_u32_e32 v28, vcc, 0x38000, v56
	s_nop 1
	v_addc_co_u32_e32 v29, vcc, 0, v57, vcc
	v_add_co_u32_e32 v32, vcc, s21, v56
	global_load_dwordx4 v[24:27], v[24:25], off nt
	s_nop 0
	global_load_dwordx4 v[28:31], v[28:29], off nt
	v_addc_co_u32_e32 v33, vcc, 0, v57, vcc
	v_add_co_u32_e32 v36, vcc, s0, v56
	s_mov_b32 s0, 0x58000
	s_nop 0
	v_addc_co_u32_e32 v37, vcc, 0, v57, vcc
	v_add_co_u32_e32 v40, vcc, s20, v56
	global_load_dwordx4 v[32:35], v[32:33], off nt
	s_nop 0
	global_load_dwordx4 v[36:39], v[36:37], off nt
	v_addc_co_u32_e32 v41, vcc, 0, v57, vcc
	v_add_co_u32_e32 v44, vcc, s0, v56
	s_mov_b32 s0, 0x68000
	s_nop 0
	v_addc_co_u32_e32 v45, vcc, 0, v57, vcc
	v_add_co_u32_e32 v48, vcc, s26, v56
	global_load_dwordx4 v[40:43], v[40:41], off nt
	s_nop 0
	global_load_dwordx4 v[44:47], v[44:45], off nt
	v_addc_co_u32_e32 v49, vcc, 0, v57, vcc
	v_add_co_u32_e32 v52, vcc, s0, v56
	s_mov_b32 s0, 0x78000
	s_nop 0
	v_addc_co_u32_e32 v53, vcc, 0, v57, vcc
	v_add_co_u32_e32 v58, vcc, s48, v56
	global_load_dwordx4 v[48:51], v[48:49], off nt
	s_nop 0
	global_load_dwordx4 v[52:55], v[52:53], off nt
	v_addc_co_u32_e32 v59, vcc, 0, v57, vcc
	v_add_co_u32_e32 v60, vcc, s0, v56
	s_nop 1
	v_addc_co_u32_e32 v61, vcc, 0, v57, vcc
	global_load_dwordx4 v[56:59], v[58:59], off nt
	s_nop 0
	global_load_dwordx4 v[60:63], v[60:61], off nt
	s_waitcnt vmcnt(15)
	ds_write2_b32 v93, v0, v1 offset1:1
	ds_write2_b32 v93, v2, v3 offset0:2 offset1:3
	v_add_u32_e32 v0, 0x410, v93
	s_waitcnt vmcnt(14)
	ds_write2_b32 v0, v4, v5 offset1:1
	v_add_u32_e32 v0, 0x418, v93
	ds_write2_b32 v0, v6, v7 offset1:1
	v_add_u32_e32 v0, 0x820, v93
	s_waitcnt vmcnt(13)
	ds_write2_b32 v0, v8, v9 offset1:1
	v_add_u32_e32 v0, 0x828, v93
	ds_write2_b32 v0, v10, v11 offset1:1
	v_add_u32_e32 v0, 0xc30, v93
	s_waitcnt vmcnt(12)
	ds_write2_b32 v0, v12, v13 offset1:1
	v_add_u32_e32 v0, 0xc38, v93
	ds_write2_b32 v0, v14, v15 offset1:1
	v_add_u32_e32 v0, 0x1040, v93
	s_waitcnt vmcnt(11)
	ds_write2_b32 v0, v16, v17 offset1:1
	v_add_u32_e32 v0, 0x1048, v93
	ds_write2_b32 v0, v18, v19 offset1:1
	v_add_u32_e32 v0, 0x1450, v93
	s_waitcnt vmcnt(10)
	ds_write2_b32 v0, v20, v21 offset1:1
	v_add_u32_e32 v0, 0x1458, v93
	ds_write2_b32 v0, v22, v23 offset1:1
	v_add_u32_e32 v0, 0x1860, v93
	s_waitcnt vmcnt(9)
	ds_write2_b32 v0, v24, v25 offset1:1
	v_add_u32_e32 v0, 0x1868, v93
	ds_write2_b32 v0, v26, v27 offset1:1
	v_add_u32_e32 v0, 0x1c70, v93
	s_waitcnt vmcnt(8)
	ds_write2_b32 v0, v28, v29 offset1:1
	v_add_u32_e32 v0, 0x1c78, v93
	ds_write2_b32 v0, v30, v31 offset1:1
	v_add_u32_e32 v0, 0x2080, v93
	s_waitcnt vmcnt(7)
	ds_write2_b32 v0, v32, v33 offset1:1
	v_add_u32_e32 v0, 0x2088, v93
	ds_write2_b32 v0, v34, v35 offset1:1
	v_add_u32_e32 v0, 0x2490, v93
	s_waitcnt vmcnt(6)
	ds_write2_b32 v0, v36, v37 offset1:1
	v_add_u32_e32 v0, 0x2498, v93
	ds_write2_b32 v0, v38, v39 offset1:1
	v_add_u32_e32 v0, 0x28a0, v93
	s_waitcnt vmcnt(5)
	ds_write2_b32 v0, v40, v41 offset1:1
	v_add_u32_e32 v0, 0x28a8, v93
	ds_write2_b32 v0, v42, v43 offset1:1
	v_add_u32_e32 v0, 0x2cb0, v93
	s_waitcnt vmcnt(4)
	ds_write2_b32 v0, v44, v45 offset1:1
	v_add_u32_e32 v0, 0x2cb8, v93
	ds_write2_b32 v0, v46, v47 offset1:1
	v_add_u32_e32 v0, 0x30c0, v93
	s_waitcnt vmcnt(3)
	ds_write2_b32 v0, v48, v49 offset1:1
	v_add_u32_e32 v0, 0x30c8, v93
	ds_write2_b32 v0, v50, v51 offset1:1
	v_add_u32_e32 v0, 0x34d0, v93
	s_waitcnt vmcnt(2)
	ds_write2_b32 v0, v52, v53 offset1:1
	v_add_u32_e32 v0, 0x34d8, v93
	ds_write2_b32 v0, v54, v55 offset1:1
	v_add_u32_e32 v0, 0x38e0, v93
	s_waitcnt vmcnt(1)
; #define LAS __attribute__((address_space(3)))
; __device__ __forceinline__ unsigned pk2(float lo, float hi) { unsigned r; asm("v_cvt_pk_bf16_f32 %0, %1, %2" : "=v"(r) : "v"(lo), "v"(hi)); return r; }
; __device__ __forceinline__ void transpose_item(const float* W, int K, int N, bf16_t* WT, int kb, int nbd, int src0, LAS float* scr, int lane, const float* gk = nullptr) {
;     ...
;         LAS float* s = scr + (4 * i + (lane >> 4)) * 65 + (lane & 15) * 4; s[0] = v[i].x; s[1] = v[i].y; s[2] = v[i].z; s[3] = v[i].w; }
;     const int c = lane & 7;
; #pragma unroll
;     for (int jj = 0; jj < 8; ++jj) {
;         const int n = (lane >> 3) + 8 * jj; const LAS float* s = scr + (8 * c) * 65 + n;
;         u32x4 o; o.x = pk2(s[0], s[65]); o.y = pk2(s[2 * 65], s[3 * 65]); o.z = pk2(s[4 * 65], s[5 * 65]); o.w = pk2(s[6 * 65], s[7 * 65]);
;         *(u32x4*)(WT + (size_t)(nbd * 64 + n) * K + k0 + 8 * c) = o;
;     }
	ds_write2_b32 v0, v56, v57 offset1:1
	v_add_u32_e32 v0, 0x38e8, v93
	ds_write2_b32 v0, v58, v59 offset1:1
	v_add_u32_e32 v0, 0x3cf0, v93
	s_waitcnt vmcnt(0)
	ds_write2_b32 v0, v60, v61 offset1:1
	v_add_u32_e32 v0, 0x3cf8, v93
	ds_write2_b32 v0, v62, v63 offset1:1
	ds_read2_b32 v[4:5], v95 offset0:65 offset1:73
	ds_read2_b32 v[6:7], v95 offset1:8
	ds_read2_b32 v[8:9], v95 offset0:130 offset1:138
	ds_read2_b32 v[10:11], v95 offset0:195 offset1:203
	v_add_u32_e32 v24, 0x400, v95
	ds_read2_b32 v[12:13], v24 offset0:4 offset1:12
	ds_read2_b32 v[14:15], v24 offset0:69 offset1:77
	ds_read2_b32 v[16:17], v24 offset0:134 offset1:142
	ds_read2_b32 v[18:19], v24 offset0:199 offset1:207
	s_waitcnt lgkmcnt(6)
	v_cvt_pk_bf16_f32 v0, v6, v4
	v_or_b32_e32 v4, s8, v94
	s_mov_b32 s7, s75
	v_mul_u32_u24_e32 v4, 0x1600, v4
	v_lshl_add_u64 v[20:21], s[6:7], 1, v[80:81]
	v_lshlrev_b32_e32 v144, 1, v4
	v_or_b32_e32 v4, s8, v96
	v_lshl_add_u64 v[22:23], v[20:21], 0, v[144:145]
	v_mul_u32_u24_e32 v4, 0x1600, v4
	s_waitcnt lgkmcnt(4)
	v_cvt_pk_bf16_f32 v1, v8, v10
	s_waitcnt lgkmcnt(2)
	v_cvt_pk_bf16_f32 v2, v12, v14
	s_waitcnt lgkmcnt(0)
	v_cvt_pk_bf16_f32 v3, v16, v18
	global_store_dwordx4 v[22:23], v[0:3], off
	v_lshlrev_b32_e32 v144, 1, v4
	s_nop 0
	v_cvt_pk_bf16_f32 v0, v7, v5
	v_cvt_pk_bf16_f32 v1, v9, v11
	v_cvt_pk_bf16_f32 v2, v13, v15
	v_cvt_pk_bf16_f32 v3, v17, v19
	v_lshl_add_u64 v[4:5], v[20:21], 0, v[144:145]
	ds_read2_b32 v[6:7], v95 offset0:16 offset1:24
	ds_read2_b32 v[8:9], v95 offset0:81 offset1:89
	ds_read2_b32 v[10:11], v95 offset0:146 offset1:154
	ds_read2_b32 v[12:13], v95 offset0:211 offset1:219
	ds_read2_b32 v[14:15], v24 offset0:20 offset1:28
	ds_read2_b32 v[16:17], v24 offset0:85 offset1:93
	ds_read2_b32 v[18:19], v24 offset0:150 offset1:158
	ds_read2_b32 v[22:23], v24 offset0:215 offset1:223
	global_store_dwordx4 v[4:5], v[0:3], off
	v_or_b32_e32 v4, s8, v97
	v_mul_u32_u24_e32 v4, 0x1600, v4
	v_lshlrev_b32_e32 v144, 1, v4
	v_lshl_add_u64 v[4:5], v[20:21], 0, v[144:145]
	s_waitcnt lgkmcnt(6)
	v_cvt_pk_bf16_f32 v0, v6, v8
	s_waitcnt lgkmcnt(4)
	v_cvt_pk_bf16_f32 v1, v10, v12
	s_waitcnt lgkmcnt(2)
	v_cvt_pk_bf16_f32 v2, v14, v16
	s_waitcnt lgkmcnt(0)
	v_cvt_pk_bf16_f32 v3, v18, v22
	global_store_dwordx4 v[4:5], v[0:3], off
	v_or_b32_e32 v4, s8, v98
	v_mul_u32_u24_e32 v4, 0x1600, v4
	v_lshlrev_b32_e32 v144, 1, v4
	v_cvt_pk_bf16_f32 v0, v7, v9
	v_cvt_pk_bf16_f32 v1, v11, v13
	v_cvt_pk_bf16_f32 v2, v15, v17
	v_cvt_pk_bf16_f32 v3, v19, v23
	v_lshl_add_u64 v[4:5], v[20:21], 0, v[144:145]
	ds_read2_b32 v[6:7], v95 offset0:32 offset1:40
	ds_read2_b32 v[8:9], v95 offset0:97 offset1:105
	ds_read2_b32 v[10:11], v95 offset0:162 offset1:170
	ds_read2_b32 v[12:13], v95 offset0:227 offset1:235
	ds_read2_b32 v[14:15], v24 offset0:36 offset1:44
	ds_read2_b32 v[16:17], v24 offset0:101 offset1:109
	ds_read2_b32 v[18:19], v24 offset0:166 offset1:174
	ds_read2_b32 v[22:23], v24 offset0:231 offset1:239
	global_store_dwordx4 v[4:5], v[0:3], off
	v_or_b32_e32 v4, s8, v99
	v_mul_u32_u24_e32 v4, 0x1600, v4
	v_lshlrev_b32_e32 v144, 1, v4
	v_lshl_add_u64 v[4:5], v[20:21], 0, v[144:145]
	s_waitcnt lgkmcnt(6)
	v_cvt_pk_bf16_f32 v0, v6, v8
	s_waitcnt lgkmcnt(4)
	v_cvt_pk_bf16_f32 v1, v10, v12
	s_waitcnt lgkmcnt(2)
	v_cvt_pk_bf16_f32 v2, v14, v16
	s_waitcnt lgkmcnt(0)
	v_cvt_pk_bf16_f32 v3, v18, v22
	global_store_dwordx4 v[4:5], v[0:3], off
	v_or_b32_e32 v4, s8, v100
	v_mul_u32_u24_e32 v4, 0x1600, v4
	v_lshlrev_b32_e32 v144, 1, v4
	v_cvt_pk_bf16_f32 v0, v7, v9
	v_cvt_pk_bf16_f32 v1, v11, v13
	v_cvt_pk_bf16_f32 v2, v15, v17
	v_cvt_pk_bf16_f32 v3, v19, v23
	v_lshl_add_u64 v[4:5], v[20:21], 0, v[144:145]
	ds_read2_b32 v[6:7], v95 offset0:48 offset1:56
	ds_read2_b32 v[8:9], v95 offset0:113 offset1:121
	ds_read2_b32 v[10:11], v95 offset0:178 offset1:186
	ds_read2_b32 v[12:13], v95 offset0:243 offset1:251
	ds_read2_b32 v[14:15], v24 offset0:52 offset1:60
	ds_read2_b32 v[16:17], v24 offset0:117 offset1:125
	ds_read2_b32 v[18:19], v24 offset0:182 offset1:190
	ds_read2_b32 v[22:23], v24 offset0:247 offset1:255
	global_store_dwordx4 v[4:5], v[0:3], off
	v_or_b32_e32 v4, s8, v101
	v_mul_u32_u24_e32 v4, 0x1600, v4
	v_lshlrev_b32_e32 v144, 1, v4
	v_lshl_add_u64 v[4:5], v[20:21], 0, v[144:145]
	s_waitcnt lgkmcnt(6)
	v_cvt_pk_bf16_f32 v0, v6, v8
	s_waitcnt lgkmcnt(4)
	v_cvt_pk_bf16_f32 v1, v10, v12
	s_waitcnt lgkmcnt(2)
	v_cvt_pk_bf16_f32 v2, v14, v16
	s_waitcnt lgkmcnt(0)
	v_cvt_pk_bf16_f32 v3, v18, v22
	global_store_dwordx4 v[4:5], v[0:3], off
	v_or_b32_e32 v4, s8, v102
	v_mul_u32_u24_e32 v4, 0x1600, v4
	v_lshlrev_b32_e32 v144, 1, v4
	v_lshl_add_u64 v[4:5], v[20:21], 0, v[144:145]
	v_cvt_pk_bf16_f32 v0, v7, v9
	v_cvt_pk_bf16_f32 v1, v11, v13
	v_cvt_pk_bf16_f32 v2, v15, v17
	v_cvt_pk_bf16_f32 v3, v19, v23
	global_store_dwordx4 v[4:5], v[0:3], off

; #define SCHED_FENCE() __builtin_amdgcn_sched_barrier(0)
; __device__ __forceinline__ void transpose_item(const float* W, int K, int N, bf16_t* WT, int kb, int nbd, int src0, LAS float* scr, int lane, const float* gk = nullptr) {
;     ...
;     const float* wp = W + (size_t)(k0 + (lane >> 4)) * N + src0 + (lane & 15) * 4;
;     f32x4 v[16];
; #pragma unroll
;     for (int i = 0; i < 16; ++i) v[i] = *(const f32x4*)(wp + (size_t)(4 * i) * N);
;     SCHED_FENCE();
; #pragma unroll
;     for (int i = 0; i < 16; ++i) { if (gk) v[i] = v[i] * gk[k0 + 4 * i + (lane >> 4)];
; __global__ void __launch_bounds__(512, 2) fwd_kernel(Args a) {
;     ...
;                 if (r < I_GU) { const int nb = r % 176; transpose_item(P.in[21], DM, NGU, (bf16_t*)(ws + WS_WGU2), r / 176, nb, map_gu(nb), scr, lane, P.in[20]); continue; } r -= I_GU;
.LBB0_310:
	s_andn2_b64 vcc, exec, s[6:7]
	s_cbranch_vccnz .LBB0_336
	s_add_i32 s6, s28, 0xea00
	s_and_b32 s7, s6, 0xffff
	s_mul_i32 s7, s7, 0xba2f
	s_lshr_b32 s7, s7, 23
	s_mul_i32 s8, s7, 0xb0
	s_sub_i32 s6, s6, s8
	s_and_b32 s8, s6, 0xffff
	s_and_b32 s6, s6, 3
	s_lshl_b32 s9, s8, 5
	s_and_b32 s9, s9, 0x1f80
	s_lshl_b32 s29, s6, 6
	s_or_b32 s30, s9, s29
	s_add_i32 s9, s29, s9
	s_addk_i32 s9, 0x1580
	s_cmp_lt_u32 s6, 2
	s_cselect_b32 s29, s30, s9
	s_lshl_b32 s9, s7, 6
	v_or_b32_e32 v64, s9, v92
	v_mov_b64_e32 v[0:1], s[78:79]
	s_mov_b32 s0, 0xb000
	v_mad_u64_u32 v[0:1], s[6:7], v64, s0, v[0:1]
	s_lshl_b32 s74, s29, 2
	v_lshl_add_u64 v[0:1], v[0:1], 0, s[74:75]
	v_lshlrev_b32_e32 v144, 2, v70
	v_lshl_add_u64 v[0:1], v[0:1], 0, v[144:145]
	s_mov_b32 s0, 0x2c000
	v_add_co_u32_e32 v2, vcc, s0, v0
	s_mov_b32 s0, 0x58000
	s_nop 0
	v_addc_co_u32_e32 v3, vcc, 0, v1, vcc
	global_load_dwordx4 v[56:59], v[0:1], off nt
	global_load_dwordx4 v[60:63], v[2:3], off nt
	v_add_co_u32_e32 v2, vcc, s0, v0
	s_mov_b32 s0, 0x84000
	s_nop 0
	v_addc_co_u32_e32 v3, vcc, 0, v1, vcc
	v_add_co_u32_e32 v4, vcc, s0, v0
	s_mov_b32 s0, 0xb0000
	s_waitcnt lgkmcnt(0)
	v_addc_co_u32_e32 v5, vcc, 0, v1, vcc
	global_load_dwordx4 v[48:51], v[2:3], off nt
	global_load_dwordx4 v[52:55], v[4:5], off nt
	v_add_co_u32_e32 v2, vcc, s0, v0
	s_mov_b32 s0, 0xdc000
	s_nop 0
	v_addc_co_u32_e32 v3, vcc, 0, v1, vcc
	v_add_co_u32_e32 v4, vcc, s0, v0
	s_mov_b32 s0, 0x108000
	s_nop 0
	v_addc_co_u32_e32 v5, vcc, 0, v1, vcc
	global_load_dwordx4 v[40:43], v[2:3], off nt
	global_load_dwordx4 v[44:47], v[4:5], off nt
	v_add_co_u32_e32 v2, vcc, s0, v0
	s_mov_b32 s0, 0x134000
	s_nop 0
	v_addc_co_u32_e32 v3, vcc, 0, v1, vcc
	v_add_co_u32_e32 v4, vcc, s0, v0
	s_mov_b32 s0, 0x160000
	s_nop 0
	v_addc_co_u32_e32 v5, vcc, 0, v1, vcc
	global_load_dwordx4 v[32:35], v[2:3], off nt
	s_waitcnt lgkmcnt(0)
	global_load_dwordx4 v[36:39], v[4:5], off nt
	v_add_co_u32_e32 v2, vcc, s0, v0
	s_mov_b32 s0, 0x18c000
	s_nop 0
	v_addc_co_u32_e32 v3, vcc, 0, v1, vcc
	v_add_co_u32_e32 v4, vcc, s0, v0
	s_mov_b32 s0, 0x1b8000
	s_nop 0
	v_addc_co_u32_e32 v5, vcc, 0, v1, vcc
	global_load_dwordx4 v[24:27], v[2:3], off nt
	global_load_dwordx4 v[28:31], v[4:5], off nt
	v_add_co_u32_e32 v2, vcc, s0, v0
	s_mov_b32 s0, 0x1e4000
	s_nop 0
	v_addc_co_u32_e32 v3, vcc, 0, v1, vcc
	v_add_co_u32_e32 v4, vcc, s0, v0
	s_mov_b32 s0, 0x210000
	s_nop 0
	v_addc_co_u32_e32 v5, vcc, 0, v1, vcc
	global_load_dwordx4 v[16:19], v[2:3], off nt
	global_load_dwordx4 v[20:23], v[4:5], off nt
	v_add_co_u32_e32 v2, vcc, s0, v0
	s_nop 1
	v_addc_co_u32_e32 v3, vcc, 0, v1, vcc
	v_add_co_u32_e32 v4, vcc, 0x23c000, v0
	s_nop 1
	v_addc_co_u32_e32 v5, vcc, 0, v1, vcc
	global_load_dwordx4 v[8:11], v[2:3], off nt
	global_load_dwordx4 v[12:15], v[4:5], off nt
	v_add_co_u32_e32 v2, vcc, 0x268000, v0
	s_nop 1
	v_addc_co_u32_e32 v3, vcc, 0, v1, vcc
	v_add_co_u32_e32 v4, vcc, 0x294000, v0
	s_nop 1
	v_addc_co_u32_e32 v5, vcc, 0, v1, vcc
	global_load_dwordx4 v[0:3], v[2:3], off nt
	s_nop 0
	global_load_dwordx4 v[4:7], v[4:5], off nt
	v_readlane_b32 s0, v251, 22
	v_readlane_b32 s1, v251, 23
	s_andn2_b64 vcc, exec, s[0:1]
	v_lshlrev_b32_e32 v90, 2, v64
	v_cndmask_b32_e64 v65, 0, 1, s[0:1]
	v_cmp_ne_u32_e64 s[38:39], 1, v65
	s_cbranch_vccnz .LBB0_370
	global_load_dword v64, v90, s[76:77]
	global_load_dword v104, v90, s[76:77] offset:16
	s_waitcnt vmcnt(1)
	v_pk_mul_f32 v[86:87], v[58:59], v[64:65] op_sel_hi:[1,0]
	v_pk_mul_f32 v[88:89], v[56:57], v[64:65] op_sel_hi:[1,0]
	s_waitcnt vmcnt(0)
	v_pk_mul_f32 v[66:67], v[62:63], v[104:105] op_sel_hi:[1,0]
	v_pk_mul_f32 v[64:65], v[60:61], v[104:105] op_sel_hi:[1,0]
	s_cbranch_execnz .LBB0_314

; #define SCHED_FENCE() __builtin_amdgcn_sched_barrier(0)
; __device__ __forceinline__ void transpose_item(const float* W, int K, int N, bf16_t* WT, int kb, int nbd, int src0, LAS float* scr, int lane, const float* gk = nullptr) {
;     ...
;     const float* wp = W + (size_t)(k0 + (lane >> 4)) * N + src0 + (lane & 15) * 4;
;     f32x4 v[16];
; #pragma unroll
;     for (int i = 0; i < 16; ++i) v[i] = *(const f32x4*)(wp + (size_t)(4 * i) * N);
;     SCHED_FENCE();
; #pragma unroll
;     for (int i = 0; i < 16; ++i) { if (gk) v[i] = v[i] * gk[k0 + 4 * i + (lane >> 4)];
; __global__ void __launch_bounds__(512, 2) fwd_kernel(Args a) {
;     ...
;                 if (r < I_GU) { const int nb = r % 176; transpose_item(P.in[3], DM, NGU, (bf16_t*)(ws + WS_WGU1), r / 176, nb, map_gu(nb), scr, lane, P.in[2]); continue; } r -= I_GU;
.LBB0_337:
	s_andn2_b64 vcc, exec, s[6:7]
	s_cbranch_vccnz .LBB0_257
	s_mul_hi_i32 s6, s28, 0x2e8ba2e9
	s_lshr_b32 s7, s6, 31
	s_ashr_i32 s29, s6, 5
	s_add_i32 s29, s29, s7
	s_mul_i32 s7, s29, 0xffffea00
	s_and_b32 s6, s28, 3
	s_add_i32 s7, s10, s7
	s_and_b32 s7, s7, 0xffffff80
	s_lshl_b32 s8, s6, 6
	s_or_b32 s9, s7, s8
	s_add_i32 s7, s8, s7
	s_addk_i32 s7, 0x1580
	s_cmp_lt_u32 s6, 2
	s_cselect_b32 s8, s9, s7
	s_lshl_b32 s6, s29, 6
	v_or_b32_e32 v64, s6, v92
	v_mov_b64_e32 v[0:1], s[54:55]
	s_mov_b32 s0, 0xb000
	v_mad_i64_i32 v[0:1], s[30:31], v64, s0, v[0:1]
	s_ashr_i32 s9, s8, 31
	v_lshl_add_u64 v[0:1], s[8:9], 2, v[0:1]
	v_lshlrev_b32_e32 v144, 2, v70
	v_lshl_add_u64 v[0:1], v[0:1], 0, v[144:145]
	s_mov_b32 s0, 0x2c000
	v_add_co_u32_e32 v2, vcc, s0, v0
	s_mov_b32 s0, 0x58000
	s_nop 0
	v_addc_co_u32_e32 v3, vcc, 0, v1, vcc
	global_load_dwordx4 v[56:59], v[0:1], off nt
	global_load_dwordx4 v[60:63], v[2:3], off nt
	v_add_co_u32_e32 v2, vcc, s0, v0
	s_mov_b32 s0, 0x84000
	s_nop 0
	v_addc_co_u32_e32 v3, vcc, 0, v1, vcc
	v_add_co_u32_e32 v4, vcc, s0, v0
	s_mov_b32 s0, 0xb0000
	s_waitcnt lgkmcnt(0)
	v_addc_co_u32_e32 v5, vcc, 0, v1, vcc
	global_load_dwordx4 v[48:51], v[2:3], off nt
	global_load_dwordx4 v[52:55], v[4:5], off nt
	v_add_co_u32_e32 v2, vcc, s0, v0
	s_mov_b32 s0, 0xdc000
	s_nop 0
	v_addc_co_u32_e32 v3, vcc, 0, v1, vcc
	v_add_co_u32_e32 v4, vcc, s0, v0
	s_mov_b32 s0, 0x108000
	s_nop 0
	v_addc_co_u32_e32 v5, vcc, 0, v1, vcc
	global_load_dwordx4 v[40:43], v[2:3], off nt
	global_load_dwordx4 v[44:47], v[4:5], off nt
	v_add_co_u32_e32 v2, vcc, s0, v0
	s_mov_b32 s0, 0x134000
	s_nop 0
	v_addc_co_u32_e32 v3, vcc, 0, v1, vcc
	v_add_co_u32_e32 v4, vcc, s0, v0
	s_mov_b32 s0, 0x160000
	s_nop 0
	v_addc_co_u32_e32 v5, vcc, 0, v1, vcc
	global_load_dwordx4 v[32:35], v[2:3], off nt
	s_waitcnt lgkmcnt(0)
	global_load_dwordx4 v[36:39], v[4:5], off nt
	v_add_co_u32_e32 v2, vcc, s0, v0
	s_mov_b32 s0, 0x18c000
	s_nop 0
	v_addc_co_u32_e32 v3, vcc, 0, v1, vcc
	v_add_co_u32_e32 v4, vcc, s0, v0
	s_mov_b32 s0, 0x1b8000
	s_nop 0
	v_addc_co_u32_e32 v5, vcc, 0, v1, vcc
	global_load_dwordx4 v[24:27], v[2:3], off nt
	global_load_dwordx4 v[28:31], v[4:5], off nt
	v_add_co_u32_e32 v2, vcc, s0, v0
	s_mov_b32 s0, 0x1e4000
	s_nop 0
	v_addc_co_u32_e32 v3, vcc, 0, v1, vcc
	v_add_co_u32_e32 v4, vcc, s0, v0
	s_mov_b32 s0, 0x210000
	s_nop 0
	v_addc_co_u32_e32 v5, vcc, 0, v1, vcc
	global_load_dwordx4 v[16:19], v[2:3], off nt
	global_load_dwordx4 v[20:23], v[4:5], off nt
	v_add_co_u32_e32 v2, vcc, s0, v0
	v_ashrrev_i32_e32 v65, 31, v64
	s_nop 0
	v_addc_co_u32_e32 v3, vcc, 0, v1, vcc
	v_add_co_u32_e32 v4, vcc, 0x23c000, v0
	s_nop 1
	v_addc_co_u32_e32 v5, vcc, 0, v1, vcc
	global_load_dwordx4 v[8:11], v[2:3], off nt
	global_load_dwordx4 v[12:15], v[4:5], off nt
	v_add_co_u32_e32 v2, vcc, 0x268000, v0
	s_nop 1
	v_addc_co_u32_e32 v3, vcc, 0, v1, vcc
	v_add_co_u32_e32 v4, vcc, 0x294000, v0
	s_nop 1
	v_addc_co_u32_e32 v5, vcc, 0, v1, vcc
	global_load_dwordx4 v[0:3], v[2:3], off nt
	s_nop 0
	global_load_dwordx4 v[4:7], v[4:5], off nt
	v_readlane_b32 s0, v251, 24
	v_readlane_b32 s1, v251, 25
	s_andn2_b64 vcc, exec, s[0:1]
	v_lshl_add_u64 v[86:87], v[64:65], 2, s[52:53]
	v_cndmask_b32_e64 v66, 0, 1, s[0:1]
	v_cmp_ne_u32_e64 s[38:39], 1, v66
	s_cbranch_vccnz .LBB0_361
	global_load_dword v64, v[86:87], off
	global_load_dword v104, v[86:87], off offset:16
	s_waitcnt vmcnt(1)
	v_pk_mul_f32 v[88:89], v[58:59], v[64:65] op_sel_hi:[1,0]
	v_pk_mul_f32 v[90:91], v[56:57], v[64:65] op_sel_hi:[1,0]
	s_waitcnt vmcnt(0)
	v_pk_mul_f32 v[66:67], v[62:63], v[104:105] op_sel_hi:[1,0]
	v_pk_mul_f32 v[64:65], v[60:61], v[104:105] op_sel_hi:[1,0]
	s_cbranch_execnz .LBB0_341

; #define SCHED_FENCE() __builtin_amdgcn_sched_barrier(0)
; __device__ __forceinline__ unsigned pk2(float lo, float hi) { unsigned r; asm("v_cvt_pk_bf16_f32 %0, %1, %2" : "=v"(r) : "v"(lo), "v"(hi)); return r; }
; __device__ __forceinline__ void x_row(const float* xr, bf16_t* h, float* rs_out, int lane) {
;     f32x4 v[8]; float s = 0.f;
; #pragma unroll
;     for (int j = 0; j < 8; ++j) v[j] = *(const f32x4*)(xr + 256 * j + 4 * lane);
;     SCHED_FENCE();
; #pragma unroll
;     for (int j = 0; j < 8; ++j) { s += (v[j].x * v[j].x + v[j].y * v[j].y) + (v[j].z * v[j].z + v[j].w * v[j].w);
;         u32x2 w; w.x = pk2(v[j].x, v[j].y); w.y = pk2(v[j].z, v[j].w); *(u32x2*)(h + 256 * j + 4 * lane) = w; }
;     const float rs = rsqrtf(wave_sum(s, lane) * (1.0f / DM) + EPS);
;     if (lane == 0) *rs_out = rs;
; }
.LBB0_392:
	s_waitcnt lgkmcnt(0)
	global_load_dwordx4 v[4:7], v[0:1], off offset:-4096 nt
	global_load_dwordx4 v[8:11], v[0:1], off offset:-3072 nt
	global_load_dwordx4 v[12:15], v[0:1], off offset:-2048 nt
	global_load_dwordx4 v[16:19], v[0:1], off offset:-1024 nt
	global_load_dwordx4 v[20:23], v[0:1], off nt
	global_load_dwordx4 v[24:27], v[0:1], off offset:1024 nt
	global_load_dwordx4 v[28:31], v[0:1], off offset:2048 nt
	global_load_dwordx4 v[32:35], v[0:1], off offset:3072 nt
	s_waitcnt vmcnt(7)
	v_mul_f32_e32 v38, v5, v5
	v_mul_f32_e32 v39, v7, v7
	v_fmac_f32_e32 v38, v4, v4
	v_fmac_f32_e32 v39, v6, v6
	v_cvt_pk_bf16_f32 v4, v4, v5
	v_cvt_pk_bf16_f32 v5, v6, v7
	s_waitcnt vmcnt(6)
	v_mul_f32_e32 v6, v9, v9
	v_mul_f32_e32 v7, v11, v11
	v_fmac_f32_e32 v6, v8, v8
	v_fmac_f32_e32 v7, v10, v10
	v_add_f32_e32 v38, v38, v39
	v_add_f32_e32 v6, v6, v7
	v_add_f32_e32 v6, v38, v6
	s_waitcnt vmcnt(5)
	v_mul_f32_e32 v7, v13, v13
	v_mul_f32_e32 v38, v15, v15
	v_fmac_f32_e32 v7, v12, v12
	v_fmac_f32_e32 v38, v14, v14
	v_add_f32_e32 v7, v7, v38
	v_add_f32_e32 v6, v6, v7
	s_waitcnt vmcnt(4)
	v_mul_f32_e32 v7, v17, v17
	v_mul_f32_e32 v38, v19, v19
	v_fmac_f32_e32 v7, v16, v16
	v_fmac_f32_e32 v38, v18, v18
	v_add_f32_e32 v7, v7, v38
	v_add_f32_e32 v6, v6, v7
	s_waitcnt vmcnt(3)
	v_mul_f32_e32 v7, v21, v21
	v_mul_f32_e32 v38, v23, v23
	v_fmac_f32_e32 v7, v20, v20
	v_fmac_f32_e32 v38, v22, v22
	v_add_f32_e32 v7, v7, v38
	v_add_f32_e32 v6, v6, v7
	s_waitcnt vmcnt(2)
	v_mul_f32_e32 v7, v25, v25
	v_mul_f32_e32 v38, v27, v27
	v_fmac_f32_e32 v7, v24, v24
	v_fmac_f32_e32 v38, v26, v26
	v_add_f32_e32 v7, v7, v38
	v_add_f32_e32 v6, v6, v7
	s_waitcnt vmcnt(1)
	v_mul_f32_e32 v7, v29, v29
	v_mul_f32_e32 v38, v31, v31
	v_fmac_f32_e32 v7, v28, v28
	v_fmac_f32_e32 v38, v30, v30
	v_add_f32_e32 v7, v7, v38
	v_add_f32_e32 v6, v6, v7
	s_waitcnt vmcnt(0)
	v_mul_f32_e32 v7, v33, v33
	v_mul_f32_e32 v38, v35, v35
	v_fmac_f32_e32 v7, v32, v32
	v_fmac_f32_e32 v38, v34, v34
	v_add_f32_e32 v7, v7, v38
	v_add_f32_e32 v38, v6, v7
	ds_bpermute_b32 v39, v70, v38
	s_waitcnt lgkmcnt(1)
	v_lshl_add_u64 v[36:37], s[66:67], 0, v[2:3]
	s_mov_b32 s8, 0xa820000
	v_add_co_u32_e64 v6, s[38:39], s8, v36
	s_nop 1
	v_addc_co_u32_e64 v7, s[38:39], 0, v37, s[38:39]
	global_store_dwordx2 v[6:7], v[4:5], off
	v_cvt_pk_bf16_f32 v4, v8, v9
	s_waitcnt lgkmcnt(0)
	v_add_f32_e32 v8, v38, v39
	ds_bpermute_b32 v9, v72, v8
	v_cvt_pk_bf16_f32 v5, v10, v11
	global_store_dwordx2 v[6:7], v[4:5], off offset:512
	v_cvt_pk_bf16_f32 v4, v12, v13
	v_cvt_pk_bf16_f32 v5, v14, v15
	s_waitcnt lgkmcnt(0)
	v_add_f32_e32 v8, v8, v9
	ds_bpermute_b32 v9, v73, v8
	global_store_dwordx2 v[6:7], v[4:5], off offset:1024
	v_cvt_pk_bf16_f32 v4, v16, v17
	v_cvt_pk_bf16_f32 v5, v18, v19
	global_store_dwordx2 v[6:7], v[4:5], off offset:1536
	s_waitcnt lgkmcnt(0)
	v_add_f32_e32 v8, v8, v9
	ds_bpermute_b32 v9, v74, v8
	v_cvt_pk_bf16_f32 v4, v20, v21
	v_cvt_pk_bf16_f32 v5, v22, v23
	global_store_dwordx2 v[6:7], v[4:5], off offset:2048
	v_cvt_pk_bf16_f32 v4, v24, v25
	s_waitcnt lgkmcnt(0)
	v_add_f32_e32 v10, v8, v9
	ds_bpermute_b32 v11, v75, v10
	v_cvt_pk_bf16_f32 v5, v26, v27
	global_store_dwordx2 v[6:7], v[4:5], off offset:2560
	v_cvt_pk_bf16_f32 v8, v28, v29
	v_cvt_pk_bf16_f32 v9, v30, v31
	s_waitcnt lgkmcnt(0)
	v_add_f32_e32 v4, v10, v11
	ds_bpermute_b32 v5, v71, v4
	global_store_dwordx2 v[6:7], v[8:9], off offset:3072
	v_cvt_pk_bf16_f32 v8, v32, v33
	v_cvt_pk_bf16_f32 v9, v34, v35
	global_store_dwordx2 v[6:7], v[8:9], off offset:3584
	s_and_saveexec_b64 s[8:9], vcc
	s_cbranch_execz .LBB0_391
	s_waitcnt lgkmcnt(0)
	v_add_f32_e32 v4, v4, v5
	v_fmamk_f32 v4, v4, 0x3a000000, v213
	v_mul_f32_e32 v5, 0x4b800000, v4
	v_cmp_gt_f32_e64 s[38:39], s45, v4
	s_add_u32 s12, s66, s6
	s_addc_u32 s13, s67, s7
	v_cndmask_b32_e64 v4, v4, v5, s[38:39]
	v_rsq_f32_e32 v4, v4
	s_nop 0
	v_mul_f32_e32 v5, 0x45800000, v4
	v_cndmask_b32_e64 v4, v4, v5, s[38:39]
	global_store_dword v145, v4, s[12:13]
	s_branch .LBB0_391

; #define SCHED_FENCE() __builtin_amdgcn_sched_barrier(0)
; __device__ __forceinline__ unsigned pk2(float lo, float hi) { unsigned r; asm("v_cvt_pk_bf16_f32 %0, %1, %2" : "=v"(r) : "v"(lo), "v"(hi)); return r; }
; __device__ __forceinline__ void norm_row_bf16(const float* xr, const float* g, bf16_t* o, int lane) {
;     f32x4 v[8], gv[8]; float s = 0.f;
; #pragma unroll
;     for (int j = 0; j < 8; ++j) { v[j] = *(const f32x4*)(xr + 256 * j + 4 * lane); gv[j] = *(const f32x4*)(g + 256 * j + 4 * lane); }
;     SCHED_FENCE();
; #pragma unroll
;     for (int j = 0; j < 8; ++j) s += (v[j].x * v[j].x + v[j].y * v[j].y) + (v[j].z * v[j].z + v[j].w * v[j].w);
;     const float rs = rsqrtf(wave_sum(s, lane) * (1.0f / DM) + EPS);
; #pragma unroll
;     for (int j = 0; j < 8; ++j) {
;         u32x2 w; w.x = pk2(v[j].x * rs * gv[j].x, v[j].y * rs * gv[j].y); w.y = pk2(v[j].z * rs * gv[j].z, v[j].w * rs * gv[j].w);
;         *(u32x2*)(o + 256 * j + 4 * lane) = w; }
; }
.LBB0_396:
	global_load_dwordx4 v[76:79], v[66:67], off offset:-4096 nt
	global_load_dwordx4 v[48:51], v[66:67], off offset:-3072 nt
	global_load_dwordx4 v[80:83], v[56:57], off nt
	global_load_dwordx4 v[52:55], v[56:57], off offset:1024 nt
	global_load_dwordx4 v[40:43], v[66:67], off offset:-2048 nt
	global_load_dwordx4 v[32:35], v[66:67], off offset:-1024 nt
	global_load_dwordx4 v[44:47], v[56:57], off offset:2048 nt
	s_waitcnt lgkmcnt(0)
	global_load_dwordx4 v[36:39], v[56:57], off offset:3072 nt
	global_load_dwordx4 v[24:27], v[66:67], off nt
	global_load_dwordx4 v[16:19], v[66:67], off offset:1024 nt
	global_load_dwordx4 v[28:31], v[58:59], off nt
	global_load_dwordx4 v[20:23], v[60:61], off nt
	global_load_dwordx4 v[8:11], v[66:67], off offset:2048 nt
	global_load_dwordx4 v[0:3], v[66:67], off offset:3072 nt
	global_load_dwordx4 v[12:15], v[62:63], off nt
	global_load_dwordx4 v[4:7], v[64:65], off nt
	s_waitcnt vmcnt(15)
	v_mov_b32_e32 v86, v77
	s_waitcnt vmcnt(14)
	v_mov_b32_e32 v87, v49
	v_mov_b32_e32 v84, v76
	v_mov_b32_e32 v85, v48
	v_pk_mul_f32 v[86:87], v[86:87], v[86:87]
	v_mov_b32_e32 v88, v79
	v_mov_b32_e32 v89, v51
	v_pk_fma_f32 v[84:85], v[84:85], v[84:85], v[86:87]
	v_mov_b32_e32 v86, v78
	v_mov_b32_e32 v87, v50
	v_pk_mul_f32 v[88:89], v[88:89], v[88:89]
	s_add_i32 s6, s6, s46
	v_pk_fma_f32 v[86:87], v[86:87], v[86:87], v[88:89]
	s_waitcnt vmcnt(11)
	v_pk_mul_f32 v[88:89], v[40:41], v[40:41]
	v_pk_add_f32 v[84:85], v[84:85], v[86:87]
	v_pk_mul_f32 v[86:87], v[42:43], v[42:43]
	v_pk_add_f32 v[84:85], v[84:85], v[84:85] op_sel:[0,1] op_sel_hi:[1,0]
	v_pk_mov_b32 v[90:91], v[88:89], v[86:87] op_sel:[1,0]
	v_mov_b32_e32 v89, v87
	v_pk_add_f32 v[86:87], v[90:91], v[88:89]
	s_waitcnt vmcnt(7)
	v_mul_f32_e32 v88, v24, v24
	v_mul_f32_e32 v89, v25, v25
	v_pk_add_f32 v[86:87], v[86:87], v[86:87] op_sel:[0,1] op_sel_hi:[1,0]
	v_mov_b32_e32 v85, v88
	v_mov_b32_e32 v87, v89
	v_pk_add_f32 v[84:85], v[84:85], v[86:87]
	v_mul_f32_e32 v86, v33, v33
	v_mul_f32_e32 v88, v35, v35
	v_mul_f32_e32 v90, v26, v26
	v_mul_f32_e32 v91, v27, v27
	v_pk_fma_f32 v[86:87], v[32:33], v[32:33], v[86:87] op_sel_hi:[1,1,0]
	v_pk_fma_f32 v[88:89], v[34:35], v[34:35], v[88:89] op_sel_hi:[1,1,0]
	v_mov_b32_e32 v87, v90
	v_mov_b32_e32 v89, v91
	v_pk_add_f32 v[86:87], v[86:87], v[88:89]
	s_waitcnt vmcnt(6)
	v_pk_mul_f32 v[88:89], v[16:17], v[16:17]
	v_pk_add_f32 v[84:85], v[84:85], v[86:87]
	v_pk_mul_f32 v[86:87], v[18:19], v[18:19]
	v_pk_add_f32 v[84:85], v[84:85], v[84:85] op_sel:[0,1] op_sel_hi:[1,0]
	v_pk_mov_b32 v[90:91], v[88:89], v[86:87] op_sel:[1,0]
	v_mov_b32_e32 v89, v87
	v_pk_add_f32 v[86:87], v[90:91], v[88:89]
	s_waitcnt vmcnt(2)
	v_mul_f32_e32 v88, v0, v0
	v_mul_f32_e32 v89, v1, v1
	v_pk_add_f32 v[86:87], v[86:87], v[86:87] op_sel:[0,1] op_sel_hi:[1,0]
	v_mov_b32_e32 v85, v88
	v_mov_b32_e32 v87, v89
	v_pk_add_f32 v[84:85], v[84:85], v[86:87]
	v_mul_f32_e32 v86, v9, v9
	v_mul_f32_e32 v88, v11, v11
	v_mul_f32_e32 v90, v2, v2
	v_mul_f32_e32 v91, v3, v3
	v_pk_fma_f32 v[86:87], v[8:9], v[8:9], v[86:87] op_sel_hi:[1,1,0]
	v_pk_fma_f32 v[88:89], v[10:11], v[10:11], v[88:89] op_sel_hi:[1,1,0]
	v_mov_b32_e32 v87, v90
	v_mov_b32_e32 v89, v91
	v_pk_add_f32 v[86:87], v[86:87], v[88:89]
	v_lshl_add_u64 v[66:67], v[66:67], 0, s[72:73]
	v_pk_add_f32 v[84:85], v[84:85], v[86:87]
	s_cmpk_gt_i32 s6, 0x3ff
	v_add_f32_e32 v84, v84, v85
	ds_bpermute_b32 v85, v70, v84
	s_waitcnt lgkmcnt(0)
	v_add_f32_e32 v84, v84, v85
	ds_bpermute_b32 v85, v72, v84
	s_waitcnt lgkmcnt(0)
	v_add_f32_e32 v84, v84, v85
	ds_bpermute_b32 v85, v73, v84
	s_waitcnt lgkmcnt(0)
	v_add_f32_e32 v84, v84, v85
	ds_bpermute_b32 v85, v74, v84
	s_waitcnt lgkmcnt(0)
	v_add_f32_e32 v84, v84, v85
	ds_bpermute_b32 v85, v75, v84
	s_waitcnt lgkmcnt(0)
	v_add_f32_e32 v84, v84, v85
	ds_bpermute_b32 v85, v71, v84
	s_waitcnt lgkmcnt(0)
	v_add_f32_e32 v84, v84, v85
	v_fmamk_f32 v84, v84, 0x3a000000, v213
	v_cmp_gt_f32_e32 vcc, s45, v84
	v_mul_f32_e32 v85, 0x4b800000, v84
	s_nop 0
	v_cndmask_b32_e32 v84, v84, v85, vcc
	v_rsq_f32_e32 v84, v84
	s_nop 0
	v_mul_f32_e32 v85, 0x45800000, v84
	v_cndmask_b32_e32 v84, v84, v85, vcc
	v_mul_f32_e32 v76, v76, v84
	v_mul_f32_e32 v77, v77, v84
	v_mul_f32_e32 v48, v48, v84
	v_mul_f32_e32 v49, v49, v84
	v_mul_f32_e32 v40, v40, v84
	v_mul_f32_e32 v41, v41, v84
	v_mul_f32_e32 v32, v32, v84
	v_mul_f32_e32 v33, v33, v84
	v_mul_f32_e32 v24, v24, v84
	v_mul_f32_e32 v25, v25, v84
	v_mul_f32_e32 v16, v16, v84
	v_mul_f32_e32 v17, v17, v84
	v_mul_f32_e32 v8, v8, v84
	v_mul_f32_e32 v9, v9, v84
	v_mul_f32_e32 v0, v0, v84
	v_mul_f32_e32 v1, v1, v84
	v_mul_f32_e32 v76, v80, v76
	v_mul_f32_e32 v77, v81, v77
	v_mul_f32_e32 v48, v52, v48
	v_mul_f32_e32 v49, v53, v49
	v_mul_f32_e32 v40, v44, v40
	v_mul_f32_e32 v41, v45, v41
	v_mul_f32_e32 v32, v36, v32
	v_mul_f32_e32 v33, v37, v33
	v_mul_f32_e32 v24, v28, v24
	v_mul_f32_e32 v25, v29, v25
	v_mul_f32_e32 v16, v20, v16
	v_mul_f32_e32 v17, v21, v17
	s_waitcnt vmcnt(1)
	v_mul_f32_e32 v8, v12, v8
	v_mul_f32_e32 v9, v13, v9
	s_waitcnt vmcnt(0)
	v_mul_f32_e32 v0, v4, v0
	v_mul_f32_e32 v1, v5, v1
	v_cvt_pk_bf16_f32 v76, v76, v77
	v_mul_f32_e32 v77, v78, v84
	v_cvt_pk_bf16_f32 v48, v48, v49
	v_mul_f32_e32 v49, v50, v84
	v_cvt_pk_bf16_f32 v40, v40, v41
	v_mul_f32_e32 v41, v42, v84
	v_cvt_pk_bf16_f32 v32, v32, v33
	v_mul_f32_e32 v33, v34, v84
	v_cvt_pk_bf16_f32 v24, v24, v25
	v_mul_f32_e32 v25, v26, v84
	v_cvt_pk_bf16_f32 v16, v16, v17
	v_mul_f32_e32 v17, v18, v84
	v_cvt_pk_bf16_f32 v8, v8, v9
	v_mul_f32_e32 v9, v10, v84
	v_cvt_pk_bf16_f32 v0, v0, v1
	v_mul_f32_e32 v1, v2, v84
	v_mul_f32_e32 v77, v82, v77
	v_mul_f32_e32 v78, v79, v84
	v_mul_f32_e32 v49, v54, v49
	v_mul_f32_e32 v50, v51, v84
	v_mul_f32_e32 v41, v46, v41
	v_mul_f32_e32 v42, v43, v84
	v_mul_f32_e32 v33, v38, v33
	v_mul_f32_e32 v34, v35, v84
	v_mul_f32_e32 v25, v30, v25
	v_mul_f32_e32 v26, v27, v84
	v_mul_f32_e32 v17, v22, v17
	v_mul_f32_e32 v18, v19, v84
	v_mul_f32_e32 v9, v14, v9
	v_mul_f32_e32 v10, v11, v84
	v_mul_f32_e32 v1, v6, v1
	v_mul_f32_e32 v2, v3, v84
	v_mul_f32_e32 v78, v83, v78
	v_cvt_pk_bf16_f32 v77, v77, v78
	global_store_dwordx2 v[68:69], v[76:77], off offset:-3584
	v_mul_f32_e32 v50, v55, v50
	v_cvt_pk_bf16_f32 v49, v49, v50
	global_store_dwordx2 v[68:69], v[48:49], off offset:-3072
	v_mul_f32_e32 v42, v47, v42
	v_cvt_pk_bf16_f32 v41, v41, v42
	global_store_dwordx2 v[68:69], v[40:41], off offset:-2560
	v_mul_f32_e32 v34, v39, v34
	v_cvt_pk_bf16_f32 v33, v33, v34
	global_store_dwordx2 v[68:69], v[32:33], off offset:-2048
	v_mul_f32_e32 v26, v31, v26
	v_cvt_pk_bf16_f32 v25, v25, v26
	global_store_dwordx2 v[68:69], v[24:25], off offset:-1536
	v_mul_f32_e32 v18, v23, v18
	v_cvt_pk_bf16_f32 v17, v17, v18
	global_store_dwordx2 v[68:69], v[16:17], off offset:-1024
	v_mul_f32_e32 v10, v15, v10
	v_cvt_pk_bf16_f32 v9, v9, v10
	global_store_dwordx2 v[68:69], v[8:9], off offset:-512
	v_mul_f32_e32 v2, v7, v2
	v_cvt_pk_bf16_f32 v1, v1, v2
	global_store_dwordx2 v[68:69], v[0:1], off
	v_lshl_add_u64 v[68:69], v[68:69], 0, s[16:17]
	s_cbranch_scc0 .LBB0_396
